# scores-to-PV hand-off uses a workgroup-scope cache invalidate (all producers and consumers are in the same workgroup) so the P tiles stay in L2; hand-written kind-0 in-projection epilogue; SGPR-base L
# speedup vs baseline: 1.0726x; 1.0100x over previous
; __device__ __forceinline__ float sigmoidf_(float x) { return __builtin_amdgcn_rcpf(1.0f + __builtin_amdgcn_exp2f(-1.44269504089f * x)); }
; __device__ __forceinline__ u32x2 pk4(f32x4 v) { u32x2 r; r.x = pk_bf16(v[0], v[1]); r.y = pk_bf16(v[2], v[3]); return r; }
; __device__ __forceinline__ int pf(int fq) { return (fq >> 1) | ((fq & 1) << 1); }
;     __device__ __forceinline__ void operator()(const f32x4 (&acc)[2][2][4][2], const Unit& u, int wr, int wc, int fr, int fq) const {
;         if (u.kind <= 2) {
;             const int chw = (u.pn & 15) * 64 + wc * 16, ch = chw + pf(fq) * 4;
;             const int rowb = u.pm * 256 + wr * 64 + fr;
;             if (u.kind == 0) {
;     ...
;             } else {
; #pragma unroll
;                 for (int ai = 0; ai < 2; ++ai) {
;                     u32x2 qv[4];
; #pragma unroll
;                     for (int m = 0; m < 4; ++m) {
;                         const f32x4 Qv = acc[ai][0][m][0], Ga = acc[ai][0][m][1], Gb = acc[ai][1][m][0], Gx = acc[ai][1][m][1]; f32x4 o1, o2, o3;
; #pragma unroll
;                         for (int j = 0; j < 4; ++j) { const float sa = sigmoidf_(Ga[j]), sb = sigmoidf_(Gb[j]), sx = sigmoidf_(Gx[j]);
;                             o1[j] = sa * __builtin_amdgcn_rcpf(fmaxf(sb, 1e-30f)); o2[j] = sb * __builtin_amdgcn_rcpf(fmaxf(sx, 1e-30f)); o3[j] = sx; }
;                         qv[m] = pk4(Qv * 0.0625f);
;                         const int c = (u.pn & 3) * 64 + wc * 16;
;                         const size_t ns = native_slot(u.pm, (u.pn & 15) >> 2, wr * 4 + ((c >> 5) & 3), ai, m, c >> 7, (c >> 4) & 1, pf(fq) * 16 + fr);
;                         __builtin_nontemporal_store(pk4(o1), (u32x2*)SGA + ns); __builtin_nontemporal_store(pk4(o2), (u32x2*)SGB + ns); __builtin_nontemporal_store(pk4(o3), (u32x2*)SGX + ns);
;                     }
; #pragma unroll
;                     for (int pr = 0; pr < 2; ++pr) store_pair16(Q + (size_t)(rowb + ai * 128 + pr * 32) * 1024 + chw, qv[2 * pr], qv[2 * pr + 1], fq);
;                 }
.LBB0_269:
	s_cmp_eq_u32 s13, 1
	s_cbranch_scc1 .Lp1e_k1
	s_cmp_eq_u32 s13, 0
	s_cbranch_scc1 .Lp1e_k0h
	s_cmp_eq_u32 s13, 2
	s_cbranch_scc0 .Lp1e_k0
	v_mbcnt_lo_u32_b32 v240, -1, 0
	v_mbcnt_hi_u32_b32 v240, -1, v240
	v_readlane_b32 s4, v255, 19
	s_nop 3
	s_lshr_b32 s4, s4, 6
	s_lshr_b32 s5, s4, 2
	s_and_b32 s30, s4, 3
	v_and_b32_e32 v241, 15, v240
	v_lshrrev_b32_e32 v242, 4, v240
	v_lshrrev_b32_e32 v243, 1, v242
	v_and_b32_e32 v244, 1, v242
	v_lshl_or_b32 v248, v244, 1, v243
	v_lshl_add_u32 v248, v248, 4, v241
	v_lshl_add_u32 v246, v243, 4, v241
	v_lshlrev_b32_e32 v243, 3, v248
	s_lshl_b32 s31, s96, 8
	s_lshl_b32 s64, s5, 6
	s_add_i32 s31, s31, s64
	v_add_u32_e32 v246, s31, v246
	v_mov_b32_e32 v247, 0
	v_lshlrev_b64 v[246:247], 11, v[246:247]
	s_and_b32 s64, s90, 15
	s_lshl_b32 s64, s64, 6
	s_lshl_b32 vcc_lo, s30, 4
	s_add_i32 s64, s64, vcc_lo
	v_lshlrev_b32_e32 v244, 3, v244
	v_add_u32_e32 v244, s64, v244
	v_lshlrev_b32_e32 v244, 1, v244
	v_mov_b32_e32 v245, 0
	v_lshl_add_u64 v[246:247], v[246:247], 0, v[244:245]
	s_lshl_b32 s64, s96, 2
	s_bfe_u32 vcc_lo, s90, 0x20002
	s_add_i32 s64, s64, vcc_lo
	s_lshl_b32 s64, s64, 17
	s_lshl_b32 vcc_lo, s5, 2
	s_and_b32 vcc_hi, s90, 1
	s_lshl_b32 vcc_hi, vcc_hi, 1
	s_add_i32 vcc_lo, vcc_lo, vcc_hi
	s_lshr_b32 vcc_hi, s30, 1
	s_add_i32 vcc_lo, vcc_lo, vcc_hi
	s_lshl_b32 vcc_lo, vcc_lo, 14
	s_add_i32 s64, s64, vcc_lo
	s_bfe_u32 vcc_lo, s90, 0x10001
	s_lshl_b32 vcc_lo, vcc_lo, 1
	s_and_b32 vcc_hi, s30, 1
	s_add_i32 vcc_lo, vcc_lo, vcc_hi
	s_lshl_b32 vcc_lo, vcc_lo, 9
	s_add_i32 s64, s64, vcc_lo
	s_mov_b32 s42, 0xbfb8aa3b
	s_mov_b32 s43, 1.0
	s_add_u32 s98, s18, s64
	s_addc_u32 s99, s19, 0
	s_add_u32 s100, s98, 0x4000000
	s_addc_u32 s101, s99, 0
	s_add_u32 s30, s20, s64
	s_addc_u32 s31, s21, 0
	s_mov_b32 vcc_lo, 0x3d800000
	s_mov_b32 vcc_hi, 0x3d800000
	v_pk_mul_f32 v[128:129], v[124:125], s[42:43] op_sel_hi:[1,0]
	v_pk_mul_f32 v[130:131], v[126:127], s[42:43] op_sel_hi:[1,0]
	v_pk_mul_f32 v[132:133], v[120:121], s[42:43] op_sel_hi:[1,0]
	v_pk_mul_f32 v[134:135], v[122:123], s[42:43] op_sel_hi:[1,0]
	v_pk_mul_f32 v[136:137], v[112:113], s[42:43] op_sel_hi:[1,0]
	v_pk_mul_f32 v[138:139], v[114:115], s[42:43] op_sel_hi:[1,0]
	v_pk_mul_f32 v[116:117], v[116:117], vcc op_sel_hi:[1,0]
	v_pk_mul_f32 v[118:119], v[118:119], vcc op_sel_hi:[1,0]
	v_exp_f32_e32 v128, v128
	v_exp_f32_e32 v129, v129
	v_exp_f32_e32 v130, v130
	v_exp_f32_e32 v131, v131
	v_exp_f32_e32 v132, v132
	v_exp_f32_e32 v133, v133
	v_exp_f32_e32 v134, v134
	v_exp_f32_e32 v135, v135
	v_exp_f32_e32 v136, v136
	v_exp_f32_e32 v137, v137
	v_exp_f32_e32 v138, v138
	v_exp_f32_e32 v139, v139
	v_pk_add_f32 v[128:129], v[128:129], s[42:43] op_sel:[0,1] op_sel_hi:[1,1]
	v_pk_add_f32 v[130:131], v[130:131], s[42:43] op_sel:[0,1] op_sel_hi:[1,1]
	v_pk_add_f32 v[132:133], v[132:133], s[42:43] op_sel:[0,1] op_sel_hi:[1,1]
	v_pk_add_f32 v[134:135], v[134:135], s[42:43] op_sel:[0,1] op_sel_hi:[1,1]
	v_pk_add_f32 v[136:137], v[136:137], s[42:43] op_sel:[0,1] op_sel_hi:[1,1]
	v_pk_add_f32 v[138:139], v[138:139], s[42:43] op_sel:[0,1] op_sel_hi:[1,1]
	v_rcp_f32_e32 v128, v128
	v_rcp_f32_e32 v129, v129
	v_rcp_f32_e32 v130, v130
	v_rcp_f32_e32 v131, v131
	v_rcp_f32_e32 v176, v132
	v_rcp_f32_e32 v177, v133
	v_rcp_f32_e32 v178, v134
	v_rcp_f32_e32 v179, v135
	v_rcp_f32_e32 v180, v136
	v_rcp_f32_e32 v181, v137
	v_rcp_f32_e32 v182, v138
	v_rcp_f32_e32 v183, v139
	v_min_f32_e32 v132, 0x7149f2ca, v132
	v_min_f32_e32 v133, 0x7149f2ca, v133
	v_min_f32_e32 v134, 0x7149f2ca, v134
	v_min_f32_e32 v135, 0x7149f2ca, v135
	v_min_f32_e32 v136, 0x7149f2ca, v136
	v_min_f32_e32 v137, 0x7149f2ca, v137
	v_min_f32_e32 v138, 0x7149f2ca, v138
	v_min_f32_e32 v139, 0x7149f2ca, v139
	v_pk_mul_f32 v[128:129], v[128:129], v[132:133]
	v_pk_mul_f32 v[130:131], v[130:131], v[134:135]
	v_pk_mul_f32 v[176:177], v[176:177], v[136:137]
	v_pk_mul_f32 v[178:179], v[178:179], v[138:139]
	v_cvt_pk_bf16_f32 v198, v116, v117
	v_cvt_pk_bf16_f32 v199, v118, v119
	v_cvt_pk_bf16_f32 v188, v180, v181
	v_cvt_pk_bf16_f32 v189, v182, v183
	v_cvt_pk_bf16_f32 v184, v128, v129
	v_cvt_pk_bf16_f32 v185, v130, v131
	v_cvt_pk_bf16_f32 v186, v176, v177
	v_cvt_pk_bf16_f32 v187, v178, v179
	global_store_dwordx2 v243, v[184:185], s[98:99] nt
	global_store_dwordx2 v243, v[186:187], s[100:101] nt
	global_store_dwordx2 v243, v[188:189], s[30:31] nt
	s_add_u32 s98, s98, 0x800
	s_addc_u32 s99, s99, 0
	s_add_u32 s100, s100, 0x800
	s_addc_u32 s101, s101, 0
	s_add_u32 s30, s30, 0x800
	s_addc_u32 s31, s31, 0
	v_pk_mul_f32 v[128:129], v[108:109], s[42:43] op_sel_hi:[1,0]
	v_pk_mul_f32 v[130:131], v[110:111], s[42:43] op_sel_hi:[1,0]
	v_pk_mul_f32 v[132:133], v[104:105], s[42:43] op_sel_hi:[1,0]
	v_pk_mul_f32 v[134:135], v[106:107], s[42:43] op_sel_hi:[1,0]
	v_pk_mul_f32 v[136:137], v[80:81], s[42:43] op_sel_hi:[1,0]
	v_pk_mul_f32 v[138:139], v[82:83], s[42:43] op_sel_hi:[1,0]
	v_pk_mul_f32 v[84:85], v[84:85], vcc op_sel_hi:[1,0]
	v_pk_mul_f32 v[86:87], v[86:87], vcc op_sel_hi:[1,0]
	v_exp_f32_e32 v128, v128
	v_exp_f32_e32 v129, v129
	v_exp_f32_e32 v130, v130
	v_exp_f32_e32 v131, v131
	v_exp_f32_e32 v132, v132
	v_exp_f32_e32 v133, v133
	v_exp_f32_e32 v134, v134
	v_exp_f32_e32 v135, v135
	v_exp_f32_e32 v136, v136
	v_exp_f32_e32 v137, v137
	v_exp_f32_e32 v138, v138
	v_exp_f32_e32 v139, v139
	v_pk_add_f32 v[128:129], v[128:129], s[42:43] op_sel:[0,1] op_sel_hi:[1,1]
	v_pk_add_f32 v[130:131], v[130:131], s[42:43] op_sel:[0,1] op_sel_hi:[1,1]
	v_pk_add_f32 v[132:133], v[132:133], s[42:43] op_sel:[0,1] op_sel_hi:[1,1]
	v_pk_add_f32 v[134:135], v[134:135], s[42:43] op_sel:[0,1] op_sel_hi:[1,1]
	v_pk_add_f32 v[136:137], v[136:137], s[42:43] op_sel:[0,1] op_sel_hi:[1,1]
; __device__ __forceinline__ float sigmoidf_(float x) { return __builtin_amdgcn_rcpf(1.0f + __builtin_amdgcn_exp2f(-1.44269504089f * x)); }
; __device__ __forceinline__ u32x2 pk4(f32x4 v) { u32x2 r; r.x = pk_bf16(v[0], v[1]); r.y = pk_bf16(v[2], v[3]); return r; }
; __device__ __forceinline__ int pf(int fq) { return (fq >> 1) | ((fq & 1) << 1); }
;     __device__ __forceinline__ void operator()(const f32x4 (&acc)[2][2][4][2], const Unit& u, int wr, int wc, int fr, int fq) const {
;     ...
;                     for (int m = 0; m < 4; ++m) {
;                         const f32x4 Qv = acc[ai][0][m][0], Ga = acc[ai][0][m][1], Gb = acc[ai][1][m][0], Gx = acc[ai][1][m][1]; f32x4 o1, o2, o3;
; #pragma unroll
;                         for (int j = 0; j < 4; ++j) { const float sa = sigmoidf_(Ga[j]), sb = sigmoidf_(Gb[j]), sx = sigmoidf_(Gx[j]);
;                             o1[j] = sa * __builtin_amdgcn_rcpf(fmaxf(sb, 1e-30f)); o2[j] = sb * __builtin_amdgcn_rcpf(fmaxf(sx, 1e-30f)); o3[j] = sx; }
;                         qv[m] = pk4(Qv * 0.0625f);
;                         const int c = (u.pn & 3) * 64 + wc * 16;
;                         const size_t ns = native_slot(u.pm, (u.pn & 15) >> 2, wr * 4 + ((c >> 5) & 3), ai, m, c >> 7, (c >> 4) & 1, pf(fq) * 16 + fr);
;                         __builtin_nontemporal_store(pk4(o1), (u32x2*)SGA + ns); __builtin_nontemporal_store(pk4(o2), (u32x2*)SGB + ns); __builtin_nontemporal_store(pk4(o3), (u32x2*)SGX + ns);
;                     }
	v_pk_add_f32 v[138:139], v[138:139], s[42:43] op_sel:[0,1] op_sel_hi:[1,1]
	v_rcp_f32_e32 v128, v128
	v_rcp_f32_e32 v129, v129
	v_rcp_f32_e32 v130, v130
	v_rcp_f32_e32 v131, v131
	v_rcp_f32_e32 v176, v132
	v_rcp_f32_e32 v177, v133
	v_rcp_f32_e32 v178, v134
	v_rcp_f32_e32 v179, v135
	v_rcp_f32_e32 v180, v136
	v_rcp_f32_e32 v181, v137
	v_rcp_f32_e32 v182, v138
	v_rcp_f32_e32 v183, v139
	v_min_f32_e32 v132, 0x7149f2ca, v132
	v_min_f32_e32 v133, 0x7149f2ca, v133
	v_min_f32_e32 v134, 0x7149f2ca, v134
	v_min_f32_e32 v135, 0x7149f2ca, v135
	v_min_f32_e32 v136, 0x7149f2ca, v136
	v_min_f32_e32 v137, 0x7149f2ca, v137
	v_min_f32_e32 v138, 0x7149f2ca, v138
	v_min_f32_e32 v139, 0x7149f2ca, v139
	v_pk_mul_f32 v[128:129], v[128:129], v[132:133]
	v_pk_mul_f32 v[130:131], v[130:131], v[134:135]
	v_pk_mul_f32 v[176:177], v[176:177], v[136:137]
	v_pk_mul_f32 v[178:179], v[178:179], v[138:139]
	v_cvt_pk_bf16_f32 v200, v84, v85
	v_cvt_pk_bf16_f32 v201, v86, v87
	v_cvt_pk_bf16_f32 v224, v180, v181
	v_cvt_pk_bf16_f32 v225, v182, v183
	v_cvt_pk_bf16_f32 v220, v128, v129
	v_cvt_pk_bf16_f32 v221, v130, v131
	v_cvt_pk_bf16_f32 v222, v176, v177
	v_cvt_pk_bf16_f32 v223, v178, v179
	global_store_dwordx2 v243, v[220:221], s[98:99] nt
	global_store_dwordx2 v243, v[222:223], s[100:101] nt
	global_store_dwordx2 v243, v[224:225], s[30:31] nt
	s_add_u32 s98, s98, 0x800
	s_addc_u32 s99, s99, 0
	s_add_u32 s100, s100, 0x800
	s_addc_u32 s101, s101, 0
	s_add_u32 s30, s30, 0x800
	s_addc_u32 s31, s31, 0
	v_pk_mul_f32 v[128:129], v[100:101], s[42:43] op_sel_hi:[1,0]
	v_pk_mul_f32 v[130:131], v[102:103], s[42:43] op_sel_hi:[1,0]
	v_pk_mul_f32 v[132:133], v[96:97], s[42:43] op_sel_hi:[1,0]
	v_pk_mul_f32 v[134:135], v[98:99], s[42:43] op_sel_hi:[1,0]
	v_pk_mul_f32 v[136:137], v[72:73], s[42:43] op_sel_hi:[1,0]
	v_pk_mul_f32 v[138:139], v[74:75], s[42:43] op_sel_hi:[1,0]
	v_pk_mul_f32 v[76:77], v[76:77], vcc op_sel_hi:[1,0]
	v_pk_mul_f32 v[78:79], v[78:79], vcc op_sel_hi:[1,0]
	v_exp_f32_e32 v128, v128
	v_exp_f32_e32 v129, v129
	v_exp_f32_e32 v130, v130
	v_exp_f32_e32 v131, v131
	v_exp_f32_e32 v132, v132
	v_exp_f32_e32 v133, v133
	v_exp_f32_e32 v134, v134
	v_exp_f32_e32 v135, v135
	v_exp_f32_e32 v136, v136
	v_exp_f32_e32 v137, v137
	v_exp_f32_e32 v138, v138
	v_exp_f32_e32 v139, v139
	v_pk_add_f32 v[128:129], v[128:129], s[42:43] op_sel:[0,1] op_sel_hi:[1,1]
	v_pk_add_f32 v[130:131], v[130:131], s[42:43] op_sel:[0,1] op_sel_hi:[1,1]
	v_pk_add_f32 v[132:133], v[132:133], s[42:43] op_sel:[0,1] op_sel_hi:[1,1]
	v_pk_add_f32 v[134:135], v[134:135], s[42:43] op_sel:[0,1] op_sel_hi:[1,1]
	v_pk_add_f32 v[136:137], v[136:137], s[42:43] op_sel:[0,1] op_sel_hi:[1,1]
	v_pk_add_f32 v[138:139], v[138:139], s[42:43] op_sel:[0,1] op_sel_hi:[1,1]
	v_rcp_f32_e32 v128, v128
	v_rcp_f32_e32 v129, v129
	v_rcp_f32_e32 v130, v130
	v_rcp_f32_e32 v131, v131
	v_rcp_f32_e32 v176, v132
	v_rcp_f32_e32 v177, v133
	v_rcp_f32_e32 v178, v134
	v_rcp_f32_e32 v179, v135
	v_rcp_f32_e32 v180, v136
	v_rcp_f32_e32 v181, v137
	v_rcp_f32_e32 v182, v138
	v_rcp_f32_e32 v183, v139
	v_min_f32_e32 v132, 0x7149f2ca, v132
	v_min_f32_e32 v133, 0x7149f2ca, v133
	v_min_f32_e32 v134, 0x7149f2ca, v134
	v_min_f32_e32 v135, 0x7149f2ca, v135
	v_min_f32_e32 v136, 0x7149f2ca, v136
	v_min_f32_e32 v137, 0x7149f2ca, v137
	v_min_f32_e32 v138, 0x7149f2ca, v138
	v_min_f32_e32 v139, 0x7149f2ca, v139
	v_pk_mul_f32 v[128:129], v[128:129], v[132:133]
	v_pk_mul_f32 v[130:131], v[130:131], v[134:135]
	v_pk_mul_f32 v[176:177], v[176:177], v[136:137]
	v_pk_mul_f32 v[178:179], v[178:179], v[138:139]
	v_cvt_pk_bf16_f32 v202, v76, v77
	v_cvt_pk_bf16_f32 v203, v78, v79
	v_cvt_pk_bf16_f32 v188, v180, v181
	v_cvt_pk_bf16_f32 v189, v182, v183
	v_cvt_pk_bf16_f32 v184, v128, v129
	v_cvt_pk_bf16_f32 v185, v130, v131
	v_cvt_pk_bf16_f32 v186, v176, v177
	v_cvt_pk_bf16_f32 v187, v178, v179
	global_store_dwordx2 v243, v[184:185], s[98:99] nt
	global_store_dwordx2 v243, v[186:187], s[100:101] nt
	global_store_dwordx2 v243, v[188:189], s[30:31] nt
	s_add_u32 s98, s98, 0x800
	s_addc_u32 s99, s99, 0
	s_add_u32 s100, s100, 0x800
	s_addc_u32 s101, s101, 0
	s_add_u32 s30, s30, 0x800
	s_addc_u32 s31, s31, 0
	v_pk_mul_f32 v[128:129], v[92:93], s[42:43] op_sel_hi:[1,0]
	v_pk_mul_f32 v[130:131], v[94:95], s[42:43] op_sel_hi:[1,0]
	v_pk_mul_f32 v[132:133], v[88:89], s[42:43] op_sel_hi:[1,0]
	v_pk_mul_f32 v[134:135], v[90:91], s[42:43] op_sel_hi:[1,0]
	v_pk_mul_f32 v[136:137], v[64:65], s[42:43] op_sel_hi:[1,0]
	v_pk_mul_f32 v[138:139], v[66:67], s[42:43] op_sel_hi:[1,0]
	v_pk_mul_f32 v[68:69], v[68:69], vcc op_sel_hi:[1,0]
	v_pk_mul_f32 v[70:71], v[70:71], vcc op_sel_hi:[1,0]
	v_exp_f32_e32 v128, v128
	v_exp_f32_e32 v129, v129
	v_exp_f32_e32 v130, v130
	v_exp_f32_e32 v131, v131
	v_exp_f32_e32 v132, v132
	v_exp_f32_e32 v133, v133
	v_exp_f32_e32 v134, v134
	v_exp_f32_e32 v135, v135
	v_exp_f32_e32 v136, v136
	v_exp_f32_e32 v137, v137
	v_exp_f32_e32 v138, v138
	v_exp_f32_e32 v139, v139
	v_pk_add_f32 v[128:129], v[128:129], s[42:43] op_sel:[0,1] op_sel_hi:[1,1]
	v_pk_add_f32 v[130:131], v[130:131], s[42:43] op_sel:[0,1] op_sel_hi:[1,1]
	v_pk_add_f32 v[132:133], v[132:133], s[42:43] op_sel:[0,1] op_sel_hi:[1,1]
	v_pk_add_f32 v[134:135], v[134:135], s[42:43] op_sel:[0,1] op_sel_hi:[1,1]
	v_pk_add_f32 v[136:137], v[136:137], s[42:43] op_sel:[0,1] op_sel_hi:[1,1]
	v_pk_add_f32 v[138:139], v[138:139], s[42:43] op_sel:[0,1] op_sel_hi:[1,1]
	v_rcp_f32_e32 v128, v128
	v_rcp_f32_e32 v129, v129
	v_rcp_f32_e32 v130, v130
	v_rcp_f32_e32 v131, v131
	v_rcp_f32_e32 v176, v132
	v_rcp_f32_e32 v177, v133
	v_rcp_f32_e32 v178, v134
	v_rcp_f32_e32 v179, v135
	v_rcp_f32_e32 v180, v136
	v_rcp_f32_e32 v181, v137
; __device__ __forceinline__ float sigmoidf_(float x) { return __builtin_amdgcn_rcpf(1.0f + __builtin_amdgcn_exp2f(-1.44269504089f * x)); }
; __device__ __forceinline__ u32x2 pk4(f32x4 v) { u32x2 r; r.x = pk_bf16(v[0], v[1]); r.y = pk_bf16(v[2], v[3]); return r; }
; __device__ __forceinline__ int pf(int fq) { return (fq >> 1) | ((fq & 1) << 1); }
;     __device__ __forceinline__ void operator()(const f32x4 (&acc)[2][2][4][2], const Unit& u, int wr, int wc, int fr, int fq) const {
;     ...
;                     for (int m = 0; m < 4; ++m) {
;                         const f32x4 Qv = acc[ai][0][m][0], Ga = acc[ai][0][m][1], Gb = acc[ai][1][m][0], Gx = acc[ai][1][m][1]; f32x4 o1, o2, o3;
; #pragma unroll
;                         for (int j = 0; j < 4; ++j) { const float sa = sigmoidf_(Ga[j]), sb = sigmoidf_(Gb[j]), sx = sigmoidf_(Gx[j]);
;                             o1[j] = sa * __builtin_amdgcn_rcpf(fmaxf(sb, 1e-30f)); o2[j] = sb * __builtin_amdgcn_rcpf(fmaxf(sx, 1e-30f)); o3[j] = sx; }
;                         qv[m] = pk4(Qv * 0.0625f);
;                         const int c = (u.pn & 3) * 64 + wc * 16;
;                         const size_t ns = native_slot(u.pm, (u.pn & 15) >> 2, wr * 4 + ((c >> 5) & 3), ai, m, c >> 7, (c >> 4) & 1, pf(fq) * 16 + fr);
;                         __builtin_nontemporal_store(pk4(o1), (u32x2*)SGA + ns); __builtin_nontemporal_store(pk4(o2), (u32x2*)SGB + ns); __builtin_nontemporal_store(pk4(o3), (u32x2*)SGX + ns);
;                     }
; #pragma unroll
;                     for (int pr = 0; pr < 2; ++pr) store_pair16(Q + (size_t)(rowb + ai * 128 + pr * 32) * 1024 + chw, qv[2 * pr], qv[2 * pr + 1], fq);
	v_rcp_f32_e32 v182, v138
	v_rcp_f32_e32 v183, v139
	v_min_f32_e32 v132, 0x7149f2ca, v132
	v_min_f32_e32 v133, 0x7149f2ca, v133
	v_min_f32_e32 v134, 0x7149f2ca, v134
	v_min_f32_e32 v135, 0x7149f2ca, v135
	v_min_f32_e32 v136, 0x7149f2ca, v136
	v_min_f32_e32 v137, 0x7149f2ca, v137
	v_min_f32_e32 v138, 0x7149f2ca, v138
	v_min_f32_e32 v139, 0x7149f2ca, v139
	v_pk_mul_f32 v[128:129], v[128:129], v[132:133]
	v_pk_mul_f32 v[130:131], v[130:131], v[134:135]
	v_pk_mul_f32 v[176:177], v[176:177], v[136:137]
	v_pk_mul_f32 v[178:179], v[178:179], v[138:139]
	v_cvt_pk_bf16_f32 v204, v68, v69
	v_cvt_pk_bf16_f32 v205, v70, v71
	v_cvt_pk_bf16_f32 v224, v180, v181
	v_cvt_pk_bf16_f32 v225, v182, v183
	v_cvt_pk_bf16_f32 v220, v128, v129
	v_cvt_pk_bf16_f32 v221, v130, v131
	v_cvt_pk_bf16_f32 v222, v176, v177
	v_cvt_pk_bf16_f32 v223, v178, v179
	global_store_dwordx2 v243, v[220:221], s[98:99] nt
	global_store_dwordx2 v243, v[222:223], s[100:101] nt
	global_store_dwordx2 v243, v[224:225], s[30:31] nt
	s_add_u32 s98, s98, 0x800
	s_addc_u32 s99, s99, 0
	s_add_u32 s100, s100, 0x800
	s_addc_u32 s101, s101, 0
	s_add_u32 s30, s30, 0x800
	s_addc_u32 s31, s31, 0
	s_nop 1
	v_permlane32_swap_b32_e32 v198, v200
	v_permlane32_swap_b32_e32 v199, v201
	v_lshl_add_u64 v[248:249], s[46:47], 0, v[246:247]
	global_store_dwordx4 v[248:249], v[198:201], off
	s_nop 1
	v_permlane32_swap_b32_e32 v202, v204
	v_permlane32_swap_b32_e32 v203, v205
	s_mov_b64 s[4:5], 0x10000
	v_lshl_add_u64 v[248:249], v[246:247], 0, s[4:5]
	v_lshl_add_u64 v[248:249], s[46:47], 0, v[248:249]
	global_store_dwordx4 v[248:249], v[202:205], off
	v_pk_mul_f32 v[128:129], v[60:61], s[42:43] op_sel_hi:[1,0]
	v_pk_mul_f32 v[130:131], v[62:63], s[42:43] op_sel_hi:[1,0]
	v_pk_mul_f32 v[132:133], v[56:57], s[42:43] op_sel_hi:[1,0]
	v_pk_mul_f32 v[134:135], v[58:59], s[42:43] op_sel_hi:[1,0]
	v_pk_mul_f32 v[136:137], v[48:49], s[42:43] op_sel_hi:[1,0]
	v_pk_mul_f32 v[138:139], v[50:51], s[42:43] op_sel_hi:[1,0]
	v_pk_mul_f32 v[52:53], v[52:53], vcc op_sel_hi:[1,0]
	v_pk_mul_f32 v[54:55], v[54:55], vcc op_sel_hi:[1,0]
	v_exp_f32_e32 v128, v128
	v_exp_f32_e32 v129, v129
	v_exp_f32_e32 v130, v130
	v_exp_f32_e32 v131, v131
	v_exp_f32_e32 v132, v132
	v_exp_f32_e32 v133, v133
	v_exp_f32_e32 v134, v134
	v_exp_f32_e32 v135, v135
	v_exp_f32_e32 v136, v136
	v_exp_f32_e32 v137, v137
	v_exp_f32_e32 v138, v138
	v_exp_f32_e32 v139, v139
	v_pk_add_f32 v[128:129], v[128:129], s[42:43] op_sel:[0,1] op_sel_hi:[1,1]
	v_pk_add_f32 v[130:131], v[130:131], s[42:43] op_sel:[0,1] op_sel_hi:[1,1]
	v_pk_add_f32 v[132:133], v[132:133], s[42:43] op_sel:[0,1] op_sel_hi:[1,1]
	v_pk_add_f32 v[134:135], v[134:135], s[42:43] op_sel:[0,1] op_sel_hi:[1,1]
	v_pk_add_f32 v[136:137], v[136:137], s[42:43] op_sel:[0,1] op_sel_hi:[1,1]
	v_pk_add_f32 v[138:139], v[138:139], s[42:43] op_sel:[0,1] op_sel_hi:[1,1]
	v_rcp_f32_e32 v128, v128
	v_rcp_f32_e32 v129, v129
	v_rcp_f32_e32 v130, v130
	v_rcp_f32_e32 v131, v131
	v_rcp_f32_e32 v176, v132
	v_rcp_f32_e32 v177, v133
	v_rcp_f32_e32 v178, v134
	v_rcp_f32_e32 v179, v135
	v_rcp_f32_e32 v180, v136
	v_rcp_f32_e32 v181, v137
	v_rcp_f32_e32 v182, v138
	v_rcp_f32_e32 v183, v139
	v_min_f32_e32 v132, 0x7149f2ca, v132
	v_min_f32_e32 v133, 0x7149f2ca, v133
	v_min_f32_e32 v134, 0x7149f2ca, v134
	v_min_f32_e32 v135, 0x7149f2ca, v135
	v_min_f32_e32 v136, 0x7149f2ca, v136
	v_min_f32_e32 v137, 0x7149f2ca, v137
	v_min_f32_e32 v138, 0x7149f2ca, v138
	v_min_f32_e32 v139, 0x7149f2ca, v139
	v_pk_mul_f32 v[128:129], v[128:129], v[132:133]
	v_pk_mul_f32 v[130:131], v[130:131], v[134:135]
	v_pk_mul_f32 v[176:177], v[176:177], v[136:137]
	v_pk_mul_f32 v[178:179], v[178:179], v[138:139]
	v_cvt_pk_bf16_f32 v198, v52, v53
	v_cvt_pk_bf16_f32 v199, v54, v55
	v_cvt_pk_bf16_f32 v188, v180, v181
	v_cvt_pk_bf16_f32 v189, v182, v183
	v_cvt_pk_bf16_f32 v184, v128, v129
	v_cvt_pk_bf16_f32 v185, v130, v131
	v_cvt_pk_bf16_f32 v186, v176, v177
	v_cvt_pk_bf16_f32 v187, v178, v179
	global_store_dwordx2 v243, v[184:185], s[98:99] nt
	global_store_dwordx2 v243, v[186:187], s[100:101] nt
	global_store_dwordx2 v243, v[188:189], s[30:31] nt
	s_add_u32 s98, s98, 0x800
	s_addc_u32 s99, s99, 0
	s_add_u32 s100, s100, 0x800
	s_addc_u32 s101, s101, 0
	s_add_u32 s30, s30, 0x800
	s_addc_u32 s31, s31, 0
	v_pk_mul_f32 v[128:129], v[44:45], s[42:43] op_sel_hi:[1,0]
	v_pk_mul_f32 v[130:131], v[46:47], s[42:43] op_sel_hi:[1,0]
	v_pk_mul_f32 v[132:133], v[40:41], s[42:43] op_sel_hi:[1,0]
	v_pk_mul_f32 v[134:135], v[42:43], s[42:43] op_sel_hi:[1,0]
	v_pk_mul_f32 v[136:137], v[16:17], s[42:43] op_sel_hi:[1,0]
	v_pk_mul_f32 v[138:139], v[18:19], s[42:43] op_sel_hi:[1,0]
	v_pk_mul_f32 v[20:21], v[20:21], vcc op_sel_hi:[1,0]
	v_pk_mul_f32 v[22:23], v[22:23], vcc op_sel_hi:[1,0]
	v_exp_f32_e32 v128, v128
	v_exp_f32_e32 v129, v129
	v_exp_f32_e32 v130, v130
	v_exp_f32_e32 v131, v131
	v_exp_f32_e32 v132, v132
	v_exp_f32_e32 v133, v133
	v_exp_f32_e32 v134, v134
	v_exp_f32_e32 v135, v135
	v_exp_f32_e32 v136, v136
	v_exp_f32_e32 v137, v137
	v_exp_f32_e32 v138, v138
	v_exp_f32_e32 v139, v139
	v_pk_add_f32 v[128:129], v[128:129], s[42:43] op_sel:[0,1] op_sel_hi:[1,1]
	v_pk_add_f32 v[130:131], v[130:131], s[42:43] op_sel:[0,1] op_sel_hi:[1,1]
	v_pk_add_f32 v[132:133], v[132:133], s[42:43] op_sel:[0,1] op_sel_hi:[1,1]
	v_pk_add_f32 v[134:135], v[134:135], s[42:43] op_sel:[0,1] op_sel_hi:[1,1]
	v_pk_add_f32 v[136:137], v[136:137], s[42:43] op_sel:[0,1] op_sel_hi:[1,1]
	v_pk_add_f32 v[138:139], v[138:139], s[42:43] op_sel:[0,1] op_sel_hi:[1,1]
	v_rcp_f32_e32 v128, v128
	v_rcp_f32_e32 v129, v129
	v_rcp_f32_e32 v130, v130
	v_rcp_f32_e32 v131, v131
	v_rcp_f32_e32 v176, v132
; __device__ __forceinline__ float sigmoidf_(float x) { return __builtin_amdgcn_rcpf(1.0f + __builtin_amdgcn_exp2f(-1.44269504089f * x)); }
; __device__ __forceinline__ u32x2 pk4(f32x4 v) { u32x2 r; r.x = pk_bf16(v[0], v[1]); r.y = pk_bf16(v[2], v[3]); return r; }
; __device__ __forceinline__ int pf(int fq) { return (fq >> 1) | ((fq & 1) << 1); }
;     __device__ __forceinline__ void operator()(const f32x4 (&acc)[2][2][4][2], const Unit& u, int wr, int wc, int fr, int fq) const {
;     ...
;                     for (int m = 0; m < 4; ++m) {
;                         const f32x4 Qv = acc[ai][0][m][0], Ga = acc[ai][0][m][1], Gb = acc[ai][1][m][0], Gx = acc[ai][1][m][1]; f32x4 o1, o2, o3;
; #pragma unroll
;                         for (int j = 0; j < 4; ++j) { const float sa = sigmoidf_(Ga[j]), sb = sigmoidf_(Gb[j]), sx = sigmoidf_(Gx[j]);
;                             o1[j] = sa * __builtin_amdgcn_rcpf(fmaxf(sb, 1e-30f)); o2[j] = sb * __builtin_amdgcn_rcpf(fmaxf(sx, 1e-30f)); o3[j] = sx; }
;                         qv[m] = pk4(Qv * 0.0625f);
;                         const int c = (u.pn & 3) * 64 + wc * 16;
;                         const size_t ns = native_slot(u.pm, (u.pn & 15) >> 2, wr * 4 + ((c >> 5) & 3), ai, m, c >> 7, (c >> 4) & 1, pf(fq) * 16 + fr);
;                         __builtin_nontemporal_store(pk4(o1), (u32x2*)SGA + ns); __builtin_nontemporal_store(pk4(o2), (u32x2*)SGB + ns); __builtin_nontemporal_store(pk4(o3), (u32x2*)SGX + ns);
;                     }
	v_rcp_f32_e32 v177, v133
	v_rcp_f32_e32 v178, v134
	v_rcp_f32_e32 v179, v135
	v_rcp_f32_e32 v180, v136
	v_rcp_f32_e32 v181, v137
	v_rcp_f32_e32 v182, v138
	v_rcp_f32_e32 v183, v139
	v_min_f32_e32 v132, 0x7149f2ca, v132
	v_min_f32_e32 v133, 0x7149f2ca, v133
	v_min_f32_e32 v134, 0x7149f2ca, v134
	v_min_f32_e32 v135, 0x7149f2ca, v135
	v_min_f32_e32 v136, 0x7149f2ca, v136
	v_min_f32_e32 v137, 0x7149f2ca, v137
	v_min_f32_e32 v138, 0x7149f2ca, v138
	v_min_f32_e32 v139, 0x7149f2ca, v139
	v_pk_mul_f32 v[128:129], v[128:129], v[132:133]
	v_pk_mul_f32 v[130:131], v[130:131], v[134:135]
	v_pk_mul_f32 v[176:177], v[176:177], v[136:137]
	v_pk_mul_f32 v[178:179], v[178:179], v[138:139]
	v_cvt_pk_bf16_f32 v200, v20, v21
	v_cvt_pk_bf16_f32 v201, v22, v23
	v_cvt_pk_bf16_f32 v224, v180, v181
	v_cvt_pk_bf16_f32 v225, v182, v183
	v_cvt_pk_bf16_f32 v220, v128, v129
	v_cvt_pk_bf16_f32 v221, v130, v131
	v_cvt_pk_bf16_f32 v222, v176, v177
	v_cvt_pk_bf16_f32 v223, v178, v179
	global_store_dwordx2 v243, v[220:221], s[98:99] nt
	global_store_dwordx2 v243, v[222:223], s[100:101] nt
	global_store_dwordx2 v243, v[224:225], s[30:31] nt
	s_add_u32 s98, s98, 0x800
	s_addc_u32 s99, s99, 0
	s_add_u32 s100, s100, 0x800
	s_addc_u32 s101, s101, 0
	s_add_u32 s30, s30, 0x800
	s_addc_u32 s31, s31, 0
	v_pk_mul_f32 v[128:129], v[36:37], s[42:43] op_sel_hi:[1,0]
	v_pk_mul_f32 v[130:131], v[38:39], s[42:43] op_sel_hi:[1,0]
	v_pk_mul_f32 v[132:133], v[32:33], s[42:43] op_sel_hi:[1,0]
	v_pk_mul_f32 v[134:135], v[34:35], s[42:43] op_sel_hi:[1,0]
	v_pk_mul_f32 v[136:137], v[8:9], s[42:43] op_sel_hi:[1,0]
	v_pk_mul_f32 v[138:139], v[10:11], s[42:43] op_sel_hi:[1,0]
	v_pk_mul_f32 v[12:13], v[12:13], vcc op_sel_hi:[1,0]
	v_pk_mul_f32 v[14:15], v[14:15], vcc op_sel_hi:[1,0]
	v_exp_f32_e32 v128, v128
	v_exp_f32_e32 v129, v129
	v_exp_f32_e32 v130, v130
	v_exp_f32_e32 v131, v131
	v_exp_f32_e32 v132, v132
	v_exp_f32_e32 v133, v133
	v_exp_f32_e32 v134, v134
	v_exp_f32_e32 v135, v135
	v_exp_f32_e32 v136, v136
	v_exp_f32_e32 v137, v137
	v_exp_f32_e32 v138, v138
	v_exp_f32_e32 v139, v139
	v_pk_add_f32 v[128:129], v[128:129], s[42:43] op_sel:[0,1] op_sel_hi:[1,1]
	v_pk_add_f32 v[130:131], v[130:131], s[42:43] op_sel:[0,1] op_sel_hi:[1,1]
	v_pk_add_f32 v[132:133], v[132:133], s[42:43] op_sel:[0,1] op_sel_hi:[1,1]
	v_pk_add_f32 v[134:135], v[134:135], s[42:43] op_sel:[0,1] op_sel_hi:[1,1]
	v_pk_add_f32 v[136:137], v[136:137], s[42:43] op_sel:[0,1] op_sel_hi:[1,1]
	v_pk_add_f32 v[138:139], v[138:139], s[42:43] op_sel:[0,1] op_sel_hi:[1,1]
	v_rcp_f32_e32 v128, v128
	v_rcp_f32_e32 v129, v129
	v_rcp_f32_e32 v130, v130
	v_rcp_f32_e32 v131, v131
	v_rcp_f32_e32 v176, v132
	v_rcp_f32_e32 v177, v133
	v_rcp_f32_e32 v178, v134
	v_rcp_f32_e32 v179, v135
	v_rcp_f32_e32 v180, v136
	v_rcp_f32_e32 v181, v137
	v_rcp_f32_e32 v182, v138
	v_rcp_f32_e32 v183, v139
	v_min_f32_e32 v132, 0x7149f2ca, v132
	v_min_f32_e32 v133, 0x7149f2ca, v133
	v_min_f32_e32 v134, 0x7149f2ca, v134
	v_min_f32_e32 v135, 0x7149f2ca, v135
	v_min_f32_e32 v136, 0x7149f2ca, v136
	v_min_f32_e32 v137, 0x7149f2ca, v137
	v_min_f32_e32 v138, 0x7149f2ca, v138
	v_min_f32_e32 v139, 0x7149f2ca, v139
	v_pk_mul_f32 v[128:129], v[128:129], v[132:133]
	v_pk_mul_f32 v[130:131], v[130:131], v[134:135]
	v_pk_mul_f32 v[176:177], v[176:177], v[136:137]
	v_pk_mul_f32 v[178:179], v[178:179], v[138:139]
	v_cvt_pk_bf16_f32 v202, v12, v13
	v_cvt_pk_bf16_f32 v203, v14, v15
	v_cvt_pk_bf16_f32 v188, v180, v181
	v_cvt_pk_bf16_f32 v189, v182, v183
	v_cvt_pk_bf16_f32 v184, v128, v129
	v_cvt_pk_bf16_f32 v185, v130, v131
; __device__ __forceinline__ float sigmoidf_(float x) { return __builtin_amdgcn_rcpf(1.0f + __builtin_amdgcn_exp2f(-1.44269504089f * x)); }
; __device__ __forceinline__ u32x2 pk4(f32x4 v) { u32x2 r; r.x = pk_bf16(v[0], v[1]); r.y = pk_bf16(v[2], v[3]); return r; }
; __device__ __forceinline__ int pf(int fq) { return (fq >> 1) | ((fq & 1) << 1); }
;     __device__ __forceinline__ void operator()(const f32x4 (&acc)[2][2][4][2], const Unit& u, int wr, int wc, int fr, int fq) const {
;     ...
;                     for (int m = 0; m < 4; ++m) {
;                         const f32x4 Qv = acc[ai][0][m][0], Ga = acc[ai][0][m][1], Gb = acc[ai][1][m][0], Gx = acc[ai][1][m][1]; f32x4 o1, o2, o3;
; #pragma unroll
;                         for (int j = 0; j < 4; ++j) { const float sa = sigmoidf_(Ga[j]), sb = sigmoidf_(Gb[j]), sx = sigmoidf_(Gx[j]);
;                             o1[j] = sa * __builtin_amdgcn_rcpf(fmaxf(sb, 1e-30f)); o2[j] = sb * __builtin_amdgcn_rcpf(fmaxf(sx, 1e-30f)); o3[j] = sx; }
;                         qv[m] = pk4(Qv * 0.0625f);
;                         const int c = (u.pn & 3) * 64 + wc * 16;
;                         const size_t ns = native_slot(u.pm, (u.pn & 15) >> 2, wr * 4 + ((c >> 5) & 3), ai, m, c >> 7, (c >> 4) & 1, pf(fq) * 16 + fr);
;                         __builtin_nontemporal_store(pk4(o1), (u32x2*)SGA + ns); __builtin_nontemporal_store(pk4(o2), (u32x2*)SGB + ns); __builtin_nontemporal_store(pk4(o3), (u32x2*)SGX + ns);
;                     }
; #pragma unroll
;                     for (int pr = 0; pr < 2; ++pr) store_pair16(Q + (size_t)(rowb + ai * 128 + pr * 32) * 1024 + chw, qv[2 * pr], qv[2 * pr + 1], fq);
	v_cvt_pk_bf16_f32 v186, v176, v177
	v_cvt_pk_bf16_f32 v187, v178, v179
	global_store_dwordx2 v243, v[184:185], s[98:99] nt
	global_store_dwordx2 v243, v[186:187], s[100:101] nt
	global_store_dwordx2 v243, v[188:189], s[30:31] nt
	s_add_u32 s98, s98, 0x800
	s_addc_u32 s99, s99, 0
	s_add_u32 s100, s100, 0x800
	s_addc_u32 s101, s101, 0
	s_add_u32 s30, s30, 0x800
	s_addc_u32 s31, s31, 0
	v_pk_mul_f32 v[128:129], v[28:29], s[42:43] op_sel_hi:[1,0]
	v_pk_mul_f32 v[130:131], v[30:31], s[42:43] op_sel_hi:[1,0]
	v_pk_mul_f32 v[132:133], v[24:25], s[42:43] op_sel_hi:[1,0]
	v_pk_mul_f32 v[134:135], v[26:27], s[42:43] op_sel_hi:[1,0]
	v_pk_mul_f32 v[136:137], v[0:1], s[42:43] op_sel_hi:[1,0]
	v_pk_mul_f32 v[138:139], v[2:3], s[42:43] op_sel_hi:[1,0]
	v_pk_mul_f32 v[4:5], v[4:5], vcc op_sel_hi:[1,0]
	v_pk_mul_f32 v[6:7], v[6:7], vcc op_sel_hi:[1,0]
	v_exp_f32_e32 v128, v128
	v_exp_f32_e32 v129, v129
	v_exp_f32_e32 v130, v130
	v_exp_f32_e32 v131, v131
	v_exp_f32_e32 v132, v132
	v_exp_f32_e32 v133, v133
	v_exp_f32_e32 v134, v134
	v_exp_f32_e32 v135, v135
	v_exp_f32_e32 v136, v136
	v_exp_f32_e32 v137, v137
	v_exp_f32_e32 v138, v138
	v_exp_f32_e32 v139, v139
	v_pk_add_f32 v[128:129], v[128:129], s[42:43] op_sel:[0,1] op_sel_hi:[1,1]
	v_pk_add_f32 v[130:131], v[130:131], s[42:43] op_sel:[0,1] op_sel_hi:[1,1]
	v_pk_add_f32 v[132:133], v[132:133], s[42:43] op_sel:[0,1] op_sel_hi:[1,1]
	v_pk_add_f32 v[134:135], v[134:135], s[42:43] op_sel:[0,1] op_sel_hi:[1,1]
	v_pk_add_f32 v[136:137], v[136:137], s[42:43] op_sel:[0,1] op_sel_hi:[1,1]
	v_pk_add_f32 v[138:139], v[138:139], s[42:43] op_sel:[0,1] op_sel_hi:[1,1]
	v_rcp_f32_e32 v128, v128
	v_rcp_f32_e32 v129, v129
	v_rcp_f32_e32 v130, v130
	v_rcp_f32_e32 v131, v131
	v_rcp_f32_e32 v176, v132
	v_rcp_f32_e32 v177, v133
	v_rcp_f32_e32 v178, v134
	v_rcp_f32_e32 v179, v135
	v_rcp_f32_e32 v180, v136
	v_rcp_f32_e32 v181, v137
	v_rcp_f32_e32 v182, v138
	v_rcp_f32_e32 v183, v139
	v_min_f32_e32 v132, 0x7149f2ca, v132
	v_min_f32_e32 v133, 0x7149f2ca, v133
	v_min_f32_e32 v134, 0x7149f2ca, v134
	v_min_f32_e32 v135, 0x7149f2ca, v135
	v_min_f32_e32 v136, 0x7149f2ca, v136
	v_min_f32_e32 v137, 0x7149f2ca, v137
	v_min_f32_e32 v138, 0x7149f2ca, v138
	v_min_f32_e32 v139, 0x7149f2ca, v139
	v_pk_mul_f32 v[128:129], v[128:129], v[132:133]
	v_pk_mul_f32 v[130:131], v[130:131], v[134:135]
	v_pk_mul_f32 v[176:177], v[176:177], v[136:137]
	v_pk_mul_f32 v[178:179], v[178:179], v[138:139]
	v_cvt_pk_bf16_f32 v204, v4, v5
	v_cvt_pk_bf16_f32 v205, v6, v7
	v_cvt_pk_bf16_f32 v224, v180, v181
	v_cvt_pk_bf16_f32 v225, v182, v183
	v_cvt_pk_bf16_f32 v220, v128, v129
	v_cvt_pk_bf16_f32 v221, v130, v131
	v_cvt_pk_bf16_f32 v222, v176, v177
	v_cvt_pk_bf16_f32 v223, v178, v179
	global_store_dwordx2 v243, v[220:221], s[98:99] nt
	global_store_dwordx2 v243, v[222:223], s[100:101] nt
	global_store_dwordx2 v243, v[224:225], s[30:31] nt
	s_add_u32 s98, s98, 0x800
	s_addc_u32 s99, s99, 0
	s_add_u32 s100, s100, 0x800
	s_addc_u32 s101, s101, 0
	s_add_u32 s30, s30, 0x800
	s_addc_u32 s31, s31, 0
	s_nop 1
	v_permlane32_swap_b32_e32 v198, v200
	v_permlane32_swap_b32_e32 v199, v201
	s_mov_b64 s[4:5], 0x40000
	v_lshl_add_u64 v[248:249], v[246:247], 0, s[4:5]
	v_lshl_add_u64 v[248:249], s[46:47], 0, v[248:249]
	global_store_dwordx4 v[248:249], v[198:201], off
	s_nop 1
	v_permlane32_swap_b32_e32 v202, v204
	v_permlane32_swap_b32_e32 v203, v205
	s_mov_b64 s[4:5], 0x50000
	v_lshl_add_u64 v[248:249], v[246:247], 0, s[4:5]
	v_lshl_add_u64 v[248:249], s[46:47], 0, v[248:249]
	global_store_dwordx4 v[248:249], v[202:205], off
	s_branch .LBB0_287

; __device__ __forceinline__ float siluf_(float x) { return x * sigmoidf_(x); }
; __device__ __forceinline__ u32x2 pk4(f32x4 v) { u32x2 r; r.x = pk_bf16(v[0], v[1]); r.y = pk_bf16(v[2], v[3]); return r; }
; template <int CTRL> __device__ __forceinline__ float dppf(float old, float v) { return __int_as_float(__builtin_amdgcn_update_dpp(__float_as_int(old), __float_as_int(v), CTRL, 0xf, 0xf, false)); }
;     __device__ __forceinline__ void operator()(const f32x4 (&acc)[2][2][4][2], const Unit& u, int wr, int wc, int fr, int fq) const {
;         if (u.kind <= 2) {
;             const int chw = (u.pn & 15) * 64 + wc * 16, ch = chw + pf(fq) * 4;
;             const int rowb = u.pm * 256 + wr * 64 + fr;
;             if (u.kind == 0) {
;                 const f32x4 w0 = *(const f32x4*)(convw + ch), w1 = *(const f32x4*)(convw + 1024 + ch), w2 = *(const f32x4*)(convw + 2048 + ch);
; #pragma unroll
;                 for (int ai = 0; ai < 2; ++ai) {
;                     const int blk = u.pm * 4 + ai * 2 + wr;
;                     f32x4 pprev = (f32x4){0.f, 0.f, 0.f, 0.f}; u32x2 hv[4];
; #pragma unroll
;                     for (int m = 0; m < 4; ++m) {
;                         const f32x4 Bv = acc[ai][0][m][0], Cv = acc[ai][0][m][1], Xv = acc[ai][1][m][0], Zv = acc[ai][1][m][1];
;                         const f32x4 p = Cv * Xv; f32x4 ga, p1, p2;
; #pragma unroll
;                         for (int j = 0; j < 4; ++j) {
;                             ga[j] = siluf_(Zv[j]) * Bv[j];
;                             const float r1 = (m > 0) ? dppf<0x121>(0.f, pprev[j]) : 0.f, r2 = (m > 0) ? dppf<0x122>(0.f, pprev[j]) : 0.f;
;                             p1[j] = dppf<0x111>(r1, p[j]); p2[j] = dppf<0x112>(r2, p[j]);
;                         }
;                         const f32x4 cv = w2 * p + w1 * p1 + w0 * p2;
;                         hv[m] = pk4(ga * cv);
;                         if (m == 3 && fr >= 14) *(u32x2*)(PAT + (size_t)(blk * 2 + (fr - 14)) * 1024 + ch) = pk4(p);
;                         if (m == 0 && fr < 2) *(u32x2*)(GAH + (size_t)(blk * 2 + fr) * 1024 + ch) = pk4(ga);
;                         pprev = p;
;                     }
; #pragma unroll
;                     for (int pr = 0; pr < 2; ++pr) store_pair16(HA + (size_t)(rowb + ai * 128 + pr * 32) * 1024 + chw, hv[2 * pr], hv[2 * pr + 1], fq);
;                 }
.Lp1e_k0h:
	v_mbcnt_lo_u32_b32 v240, -1, 0
	v_mbcnt_hi_u32_b32 v240, -1, v240
	v_readlane_b32 s4, v255, 19
	v_readlane_b32 s98, v255, 27
	v_readlane_b32 s99, v255, 28
	v_readlane_b32 s100, v255, 29
	v_readlane_b32 s101, v255, 30
	v_and_b32_e32 v241, 15, v240
	v_lshrrev_b32_e32 v242, 4, v240
	s_lshr_b32 s4, s4, 6
	s_lshr_b32 s5, s4, 2
	s_and_b32 s30, s4, 3
	s_and_b32 s64, s90, 15
	s_lshl_b32 s64, s64, 6
	s_lshl_b32 vcc_lo, s30, 4
	s_add_i32 s64, s64, vcc_lo
	v_lshrrev_b32_e32 v213, 1, v242
	v_and_b32_e32 v214, 1, v242
	v_lshl_or_b32 v210, v214, 1, v213
	v_lshl_add_u32 v210, v210, 2, s64
	v_lshlrev_b32_e32 v211, 1, v210
	v_lshlrev_b32_e32 v210, 2, v210
	global_load_dwordx4 v[176:179], v210, s[44:45]
	global_load_dwordx4 v[180:183], v210, s[98:99]
	global_load_dwordx4 v[184:187], v210, s[100:101]
	s_lshl_b32 s31, s96, 8
	s_lshl_b32 vcc_lo, s5, 6
	s_add_i32 s31, s31, vcc_lo
	v_lshl_add_u32 v212, v213, 4, v241
	v_add_u32_e32 v212, s31, v212
	v_lshlrev_b32_e32 v212, 11, v212
	v_lshl_add_u32 v214, v214, 3, s64
	v_lshl_add_u32 v212, v214, 1, v212
	s_lshl_b32 s31, s96, 3
	s_lshl_b32 vcc_lo, s5, 1
	s_add_i32 s31, s31, vcc_lo
	v_add_u32_e32 v213, s31, v241
	v_lshl_add_u32 v211, v213, 11, v211
	v_readlane_b32 s98, v255, 11
	v_readlane_b32 s99, v255, 12
	s_mov_b32 s42, 0xbfb8aa3b
	s_mov_b32 s43, 1.0
	v_pk_mul_f32 v[128:129], v[112:113], s[42:43] op_sel_hi:[1,0]
	v_pk_mul_f32 v[130:131], v[114:115], s[42:43] op_sel_hi:[1,0]
	v_pk_mul_f32 v[120:121], v[124:125], v[120:121]
	v_pk_mul_f32 v[122:123], v[126:127], v[122:123]
	v_exp_f32_e32 v128, v128
	v_exp_f32_e32 v129, v129
	v_exp_f32_e32 v130, v130
	v_exp_f32_e32 v131, v131
	v_mov_b32_e32 v132, 0
	v_mov_b32_e32 v136, 0
	v_mov_b32_e32 v133, 0
	v_mov_b32_e32 v137, 0
	v_mov_b32_e32 v134, 0
	v_mov_b32_e32 v138, 0
	v_mov_b32_e32 v135, 0
	v_mov_b32_e32 v139, 0
	v_pk_add_f32 v[128:129], v[128:129], s[42:43] op_sel:[0,1] op_sel_hi:[1,1]
	v_pk_add_f32 v[130:131], v[130:131], s[42:43] op_sel:[0,1] op_sel_hi:[1,1]
	v_mov_b32_dpp v132, v120 row_shr:1 row_mask:0xf bank_mask:0xf
	v_mov_b32_dpp v136, v120 row_shr:2 row_mask:0xf bank_mask:0xf
	v_mov_b32_dpp v133, v121 row_shr:1 row_mask:0xf bank_mask:0xf
	v_mov_b32_dpp v137, v121 row_shr:2 row_mask:0xf bank_mask:0xf
	v_mov_b32_dpp v134, v122 row_shr:1 row_mask:0xf bank_mask:0xf
	v_mov_b32_dpp v138, v122 row_shr:2 row_mask:0xf bank_mask:0xf
	v_mov_b32_dpp v135, v123 row_shr:1 row_mask:0xf bank_mask:0xf
	v_mov_b32_dpp v139, v123 row_shr:2 row_mask:0xf bank_mask:0xf
	v_rcp_f32_e32 v128, v128
	v_rcp_f32_e32 v129, v129
	v_rcp_f32_e32 v130, v130
	v_rcp_f32_e32 v131, v131
	s_waitcnt vmcnt(0)
	v_pk_mul_f32 v[132:133], v[180:181], v[132:133]
	v_pk_mul_f32 v[134:135], v[182:183], v[134:135]
	v_pk_mul_f32 v[128:129], v[112:113], v[128:129]
	v_pk_mul_f32 v[130:131], v[114:115], v[130:131]
	v_pk_fma_f32 v[132:133], v[184:185], v[120:121], v[132:133]
	v_pk_fma_f32 v[134:135], v[186:187], v[122:123], v[134:135]
	v_pk_mul_f32 v[116:117], v[116:117], v[128:129]
	v_pk_mul_f32 v[118:119], v[118:119], v[130:131]
	v_pk_fma_f32 v[132:133], v[176:177], v[136:137], v[132:133]
	v_pk_fma_f32 v[134:135], v[178:179], v[138:139], v[134:135]
	v_cvt_pk_bf16_f32 v208, v116, v117
	v_cvt_pk_bf16_f32 v209, v118, v119
	v_pk_mul_f32 v[132:133], v[116:117], v[132:133]
	v_pk_mul_f32 v[134:135], v[118:119], v[134:135]
	v_cmp_gt_u32_e32 vcc, 2, v241
	s_add_u32 s100, s60, 0x0
	s_addc_u32 s101, s61, 0
	s_nop 2
	s_and_saveexec_b64 s[4:5], vcc
	global_store_dwordx2 v211, v[208:209], s[100:101]
	s_mov_b64 exec, s[4:5]
	v_cvt_pk_bf16_f32 v198, v132, v133
	v_cvt_pk_bf16_f32 v199, v134, v135
	v_pk_mul_f32 v[128:129], v[80:81], s[42:43] op_sel_hi:[1,0]
	v_pk_mul_f32 v[130:131], v[82:83], s[42:43] op_sel_hi:[1,0]
	v_pk_mul_f32 v[104:105], v[108:109], v[104:105]
	v_pk_mul_f32 v[106:107], v[110:111], v[106:107]
	v_exp_f32_e32 v128, v128
	v_exp_f32_e32 v129, v129
	v_exp_f32_e32 v130, v130
	v_exp_f32_e32 v131, v131
	v_mov_b32_dpp v132, v120 row_ror:1 row_mask:0xf bank_mask:0xf
	v_mov_b32_dpp v136, v120 row_ror:2 row_mask:0xf bank_mask:0xf
	v_mov_b32_dpp v133, v121 row_ror:1 row_mask:0xf bank_mask:0xf
	v_mov_b32_dpp v137, v121 row_ror:2 row_mask:0xf bank_mask:0xf
	v_mov_b32_dpp v134, v122 row_ror:1 row_mask:0xf bank_mask:0xf
	v_mov_b32_dpp v138, v122 row_ror:2 row_mask:0xf bank_mask:0xf
	v_mov_b32_dpp v135, v123 row_ror:1 row_mask:0xf bank_mask:0xf
	v_mov_b32_dpp v139, v123 row_ror:2 row_mask:0xf bank_mask:0xf
	v_pk_add_f32 v[128:129], v[128:129], s[42:43] op_sel:[0,1] op_sel_hi:[1,1]
	v_pk_add_f32 v[130:131], v[130:131], s[42:43] op_sel:[0,1] op_sel_hi:[1,1]
	v_mov_b32_dpp v132, v104 row_shr:1 row_mask:0xf bank_mask:0xf
	v_mov_b32_dpp v136, v104 row_shr:2 row_mask:0xf bank_mask:0xf
	v_mov_b32_dpp v133, v105 row_shr:1 row_mask:0xf bank_mask:0xf
	v_mov_b32_dpp v137, v105 row_shr:2 row_mask:0xf bank_mask:0xf
	v_mov_b32_dpp v134, v106 row_shr:1 row_mask:0xf bank_mask:0xf
	v_mov_b32_dpp v138, v106 row_shr:2 row_mask:0xf bank_mask:0xf
	v_mov_b32_dpp v135, v107 row_shr:1 row_mask:0xf bank_mask:0xf
	v_mov_b32_dpp v139, v107 row_shr:2 row_mask:0xf bank_mask:0xf
	v_rcp_f32_e32 v128, v128
	v_rcp_f32_e32 v129, v129
	v_rcp_f32_e32 v130, v130
	v_rcp_f32_e32 v131, v131
	v_pk_mul_f32 v[132:133], v[180:181], v[132:133]
	v_pk_mul_f32 v[134:135], v[182:183], v[134:135]
	v_pk_mul_f32 v[128:129], v[80:81], v[128:129]
	v_pk_mul_f32 v[130:131], v[82:83], v[130:131]
	v_pk_fma_f32 v[132:133], v[184:185], v[104:105], v[132:133]
	v_pk_fma_f32 v[134:135], v[186:187], v[106:107], v[134:135]
	v_pk_mul_f32 v[84:85], v[84:85], v[128:129]
	v_pk_mul_f32 v[86:87], v[86:87], v[130:131]
	v_pk_fma_f32 v[132:133], v[176:177], v[136:137], v[132:133]
; __device__ __forceinline__ float siluf_(float x) { return x * sigmoidf_(x); }
; __device__ __forceinline__ u32x2 pk4(f32x4 v) { u32x2 r; r.x = pk_bf16(v[0], v[1]); r.y = pk_bf16(v[2], v[3]); return r; }
; template <int CTRL> __device__ __forceinline__ float dppf(float old, float v) { return __int_as_float(__builtin_amdgcn_update_dpp(__float_as_int(old), __float_as_int(v), CTRL, 0xf, 0xf, false)); }
;     __device__ __forceinline__ void operator()(const f32x4 (&acc)[2][2][4][2], const Unit& u, int wr, int wc, int fr, int fq) const {
;         if (u.kind <= 2) {
;             const int chw = (u.pn & 15) * 64 + wc * 16, ch = chw + pf(fq) * 4;
;             const int rowb = u.pm * 256 + wr * 64 + fr;
;             if (u.kind == 0) {
;                 const f32x4 w0 = *(const f32x4*)(convw + ch), w1 = *(const f32x4*)(convw + 1024 + ch), w2 = *(const f32x4*)(convw + 2048 + ch);
; #pragma unroll
;                 for (int ai = 0; ai < 2; ++ai) {
;                     const int blk = u.pm * 4 + ai * 2 + wr;
;                     f32x4 pprev = (f32x4){0.f, 0.f, 0.f, 0.f}; u32x2 hv[4];
; #pragma unroll
;                     for (int m = 0; m < 4; ++m) {
;                         const f32x4 Bv = acc[ai][0][m][0], Cv = acc[ai][0][m][1], Xv = acc[ai][1][m][0], Zv = acc[ai][1][m][1];
;                         const f32x4 p = Cv * Xv; f32x4 ga, p1, p2;
; #pragma unroll
;                         for (int j = 0; j < 4; ++j) {
;                             ga[j] = siluf_(Zv[j]) * Bv[j];
;                             const float r1 = (m > 0) ? dppf<0x121>(0.f, pprev[j]) : 0.f, r2 = (m > 0) ? dppf<0x122>(0.f, pprev[j]) : 0.f;
;                             p1[j] = dppf<0x111>(r1, p[j]); p2[j] = dppf<0x112>(r2, p[j]);
;                         }
;                         const f32x4 cv = w2 * p + w1 * p1 + w0 * p2;
;                         hv[m] = pk4(ga * cv);
;                         if (m == 3 && fr >= 14) *(u32x2*)(PAT + (size_t)(blk * 2 + (fr - 14)) * 1024 + ch) = pk4(p);
;                         if (m == 0 && fr < 2) *(u32x2*)(GAH + (size_t)(blk * 2 + fr) * 1024 + ch) = pk4(ga);
;                         pprev = p;
;                     }
; #pragma unroll
;                     for (int pr = 0; pr < 2; ++pr) store_pair16(HA + (size_t)(rowb + ai * 128 + pr * 32) * 1024 + chw, hv[2 * pr], hv[2 * pr + 1], fq);
;                 }
	v_pk_fma_f32 v[134:135], v[178:179], v[138:139], v[134:135]
	v_pk_mul_f32 v[132:133], v[84:85], v[132:133]
	v_pk_mul_f32 v[134:135], v[86:87], v[134:135]
	v_cvt_pk_bf16_f32 v200, v132, v133
	v_cvt_pk_bf16_f32 v201, v134, v135
	v_pk_mul_f32 v[128:129], v[72:73], s[42:43] op_sel_hi:[1,0]
	v_pk_mul_f32 v[130:131], v[74:75], s[42:43] op_sel_hi:[1,0]
	v_pk_mul_f32 v[96:97], v[100:101], v[96:97]
	v_pk_mul_f32 v[98:99], v[102:103], v[98:99]
	v_exp_f32_e32 v128, v128
	v_exp_f32_e32 v129, v129
	v_exp_f32_e32 v130, v130
	v_exp_f32_e32 v131, v131
	v_mov_b32_dpp v132, v104 row_ror:1 row_mask:0xf bank_mask:0xf
	v_mov_b32_dpp v136, v104 row_ror:2 row_mask:0xf bank_mask:0xf
	v_mov_b32_dpp v133, v105 row_ror:1 row_mask:0xf bank_mask:0xf
	v_mov_b32_dpp v137, v105 row_ror:2 row_mask:0xf bank_mask:0xf
	v_mov_b32_dpp v134, v106 row_ror:1 row_mask:0xf bank_mask:0xf
	v_mov_b32_dpp v138, v106 row_ror:2 row_mask:0xf bank_mask:0xf
	v_mov_b32_dpp v135, v107 row_ror:1 row_mask:0xf bank_mask:0xf
	v_mov_b32_dpp v139, v107 row_ror:2 row_mask:0xf bank_mask:0xf
	v_pk_add_f32 v[128:129], v[128:129], s[42:43] op_sel:[0,1] op_sel_hi:[1,1]
	v_pk_add_f32 v[130:131], v[130:131], s[42:43] op_sel:[0,1] op_sel_hi:[1,1]
	v_mov_b32_dpp v132, v96 row_shr:1 row_mask:0xf bank_mask:0xf
	v_mov_b32_dpp v136, v96 row_shr:2 row_mask:0xf bank_mask:0xf
	v_mov_b32_dpp v133, v97 row_shr:1 row_mask:0xf bank_mask:0xf
	v_mov_b32_dpp v137, v97 row_shr:2 row_mask:0xf bank_mask:0xf
	v_mov_b32_dpp v134, v98 row_shr:1 row_mask:0xf bank_mask:0xf
	v_mov_b32_dpp v138, v98 row_shr:2 row_mask:0xf bank_mask:0xf
	v_mov_b32_dpp v135, v99 row_shr:1 row_mask:0xf bank_mask:0xf
	v_mov_b32_dpp v139, v99 row_shr:2 row_mask:0xf bank_mask:0xf
	v_rcp_f32_e32 v128, v128
	v_rcp_f32_e32 v129, v129
	v_rcp_f32_e32 v130, v130
	v_rcp_f32_e32 v131, v131
	v_pk_mul_f32 v[132:133], v[180:181], v[132:133]
	v_pk_mul_f32 v[134:135], v[182:183], v[134:135]
	v_pk_mul_f32 v[128:129], v[72:73], v[128:129]
	v_pk_mul_f32 v[130:131], v[74:75], v[130:131]
	v_pk_fma_f32 v[132:133], v[184:185], v[96:97], v[132:133]
	v_pk_fma_f32 v[134:135], v[186:187], v[98:99], v[134:135]
	v_pk_mul_f32 v[76:77], v[76:77], v[128:129]
	v_pk_mul_f32 v[78:79], v[78:79], v[130:131]
	v_pk_fma_f32 v[132:133], v[176:177], v[136:137], v[132:133]
	v_pk_fma_f32 v[134:135], v[178:179], v[138:139], v[134:135]
	v_pk_mul_f32 v[132:133], v[76:77], v[132:133]
	v_pk_mul_f32 v[134:135], v[78:79], v[134:135]
	v_cvt_pk_bf16_f32 v202, v132, v133
	v_cvt_pk_bf16_f32 v203, v134, v135
	v_pk_mul_f32 v[128:129], v[64:65], s[42:43] op_sel_hi:[1,0]
	v_pk_mul_f32 v[130:131], v[66:67], s[42:43] op_sel_hi:[1,0]
	v_pk_mul_f32 v[88:89], v[92:93], v[88:89]
	v_pk_mul_f32 v[90:91], v[94:95], v[90:91]
	v_exp_f32_e32 v128, v128
	v_exp_f32_e32 v129, v129
	v_exp_f32_e32 v130, v130
	v_exp_f32_e32 v131, v131
	v_mov_b32_dpp v132, v96 row_ror:1 row_mask:0xf bank_mask:0xf
	v_mov_b32_dpp v136, v96 row_ror:2 row_mask:0xf bank_mask:0xf
	v_mov_b32_dpp v133, v97 row_ror:1 row_mask:0xf bank_mask:0xf
	v_mov_b32_dpp v137, v97 row_ror:2 row_mask:0xf bank_mask:0xf
	v_mov_b32_dpp v134, v98 row_ror:1 row_mask:0xf bank_mask:0xf
	v_mov_b32_dpp v138, v98 row_ror:2 row_mask:0xf bank_mask:0xf
	v_mov_b32_dpp v135, v99 row_ror:1 row_mask:0xf bank_mask:0xf
	v_mov_b32_dpp v139, v99 row_ror:2 row_mask:0xf bank_mask:0xf
	v_pk_add_f32 v[128:129], v[128:129], s[42:43] op_sel:[0,1] op_sel_hi:[1,1]
	v_pk_add_f32 v[130:131], v[130:131], s[42:43] op_sel:[0,1] op_sel_hi:[1,1]
	v_mov_b32_dpp v132, v88 row_shr:1 row_mask:0xf bank_mask:0xf
	v_mov_b32_dpp v136, v88 row_shr:2 row_mask:0xf bank_mask:0xf
	v_mov_b32_dpp v133, v89 row_shr:1 row_mask:0xf bank_mask:0xf
	v_mov_b32_dpp v137, v89 row_shr:2 row_mask:0xf bank_mask:0xf
	v_mov_b32_dpp v134, v90 row_shr:1 row_mask:0xf bank_mask:0xf
	v_mov_b32_dpp v138, v90 row_shr:2 row_mask:0xf bank_mask:0xf
	v_mov_b32_dpp v135, v91 row_shr:1 row_mask:0xf bank_mask:0xf
	v_mov_b32_dpp v139, v91 row_shr:2 row_mask:0xf bank_mask:0xf
	v_rcp_f32_e32 v128, v128
	v_rcp_f32_e32 v129, v129
	v_rcp_f32_e32 v130, v130
	v_rcp_f32_e32 v131, v131
	v_pk_mul_f32 v[132:133], v[180:181], v[132:133]
	v_pk_mul_f32 v[134:135], v[182:183], v[134:135]
	v_pk_mul_f32 v[128:129], v[64:65], v[128:129]
	v_pk_mul_f32 v[130:131], v[66:67], v[130:131]
	v_pk_fma_f32 v[132:133], v[184:185], v[88:89], v[132:133]
	v_pk_fma_f32 v[134:135], v[186:187], v[90:91], v[134:135]
	v_pk_mul_f32 v[68:69], v[68:69], v[128:129]
	v_pk_mul_f32 v[70:71], v[70:71], v[130:131]
	v_pk_fma_f32 v[132:133], v[176:177], v[136:137], v[132:133]
	v_pk_fma_f32 v[134:135], v[178:179], v[138:139], v[134:135]
	v_cvt_pk_bf16_f32 v206, v88, v89
	v_cvt_pk_bf16_f32 v207, v90, v91
	v_pk_mul_f32 v[132:133], v[68:69], v[132:133]
	v_pk_mul_f32 v[134:135], v[70:71], v[134:135]
	v_cmp_lt_u32_e32 vcc, 13, v241
	s_sub_u32 s100, s58, 0x7000
	s_subb_u32 s101, s59, 0
	s_nop 2
	s_and_saveexec_b64 s[4:5], vcc
	global_store_dwordx2 v211, v[206:207], s[100:101]
	s_mov_b64 exec, s[4:5]
	v_cvt_pk_bf16_f32 v204, v132, v133
	v_cvt_pk_bf16_f32 v205, v134, v135
	s_add_u32 s100, s98, 0x0
	s_addc_u32 s101, s99, 0
	v_permlane32_swap_b32_e32 v198, v200
	v_permlane32_swap_b32_e32 v199, v201
	global_store_dwordx4 v212, v[198:201], s[100:101]
	s_add_u32 s100, s98, 0x10000
	s_addc_u32 s101, s99, 0
	v_permlane32_swap_b32_e32 v202, v204
	v_permlane32_swap_b32_e32 v203, v205
	global_store_dwordx4 v212, v[202:205], s[100:101]
	v_pk_mul_f32 v[128:129], v[48:49], s[42:43] op_sel_hi:[1,0]
	v_pk_mul_f32 v[130:131], v[50:51], s[42:43] op_sel_hi:[1,0]
	v_pk_mul_f32 v[56:57], v[60:61], v[56:57]
	v_pk_mul_f32 v[58:59], v[62:63], v[58:59]
	v_exp_f32_e32 v128, v128
	v_exp_f32_e32 v129, v129
	v_exp_f32_e32 v130, v130
; __device__ __forceinline__ float siluf_(float x) { return x * sigmoidf_(x); }
; __device__ __forceinline__ u32x2 pk4(f32x4 v) { u32x2 r; r.x = pk_bf16(v[0], v[1]); r.y = pk_bf16(v[2], v[3]); return r; }
; template <int CTRL> __device__ __forceinline__ float dppf(float old, float v) { return __int_as_float(__builtin_amdgcn_update_dpp(__float_as_int(old), __float_as_int(v), CTRL, 0xf, 0xf, false)); }
;     __device__ __forceinline__ void operator()(const f32x4 (&acc)[2][2][4][2], const Unit& u, int wr, int wc, int fr, int fq) const {
;         if (u.kind <= 2) {
;             const int chw = (u.pn & 15) * 64 + wc * 16, ch = chw + pf(fq) * 4;
;             const int rowb = u.pm * 256 + wr * 64 + fr;
;             if (u.kind == 0) {
;                 const f32x4 w0 = *(const f32x4*)(convw + ch), w1 = *(const f32x4*)(convw + 1024 + ch), w2 = *(const f32x4*)(convw + 2048 + ch);
; #pragma unroll
;                 for (int ai = 0; ai < 2; ++ai) {
;                     const int blk = u.pm * 4 + ai * 2 + wr;
;                     f32x4 pprev = (f32x4){0.f, 0.f, 0.f, 0.f}; u32x2 hv[4];
; #pragma unroll
;                     for (int m = 0; m < 4; ++m) {
;                         const f32x4 Bv = acc[ai][0][m][0], Cv = acc[ai][0][m][1], Xv = acc[ai][1][m][0], Zv = acc[ai][1][m][1];
;                         const f32x4 p = Cv * Xv; f32x4 ga, p1, p2;
; #pragma unroll
;                         for (int j = 0; j < 4; ++j) {
;                             ga[j] = siluf_(Zv[j]) * Bv[j];
;                             const float r1 = (m > 0) ? dppf<0x121>(0.f, pprev[j]) : 0.f, r2 = (m > 0) ? dppf<0x122>(0.f, pprev[j]) : 0.f;
;                             p1[j] = dppf<0x111>(r1, p[j]); p2[j] = dppf<0x112>(r2, p[j]);
;                         }
;                         const f32x4 cv = w2 * p + w1 * p1 + w0 * p2;
;                         hv[m] = pk4(ga * cv);
;                         if (m == 3 && fr >= 14) *(u32x2*)(PAT + (size_t)(blk * 2 + (fr - 14)) * 1024 + ch) = pk4(p);
;                         if (m == 0 && fr < 2) *(u32x2*)(GAH + (size_t)(blk * 2 + fr) * 1024 + ch) = pk4(ga);
;                         pprev = p;
;                     }
; #pragma unroll
;                     for (int pr = 0; pr < 2; ++pr) store_pair16(HA + (size_t)(rowb + ai * 128 + pr * 32) * 1024 + chw, hv[2 * pr], hv[2 * pr + 1], fq);
;                 }
	v_exp_f32_e32 v131, v131
	v_mov_b32_e32 v132, 0
	v_mov_b32_e32 v136, 0
	v_mov_b32_e32 v133, 0
	v_mov_b32_e32 v137, 0
	v_mov_b32_e32 v134, 0
	v_mov_b32_e32 v138, 0
	v_mov_b32_e32 v135, 0
	v_mov_b32_e32 v139, 0
	v_pk_add_f32 v[128:129], v[128:129], s[42:43] op_sel:[0,1] op_sel_hi:[1,1]
	v_pk_add_f32 v[130:131], v[130:131], s[42:43] op_sel:[0,1] op_sel_hi:[1,1]
	v_mov_b32_dpp v132, v56 row_shr:1 row_mask:0xf bank_mask:0xf
	v_mov_b32_dpp v136, v56 row_shr:2 row_mask:0xf bank_mask:0xf
	v_mov_b32_dpp v133, v57 row_shr:1 row_mask:0xf bank_mask:0xf
	v_mov_b32_dpp v137, v57 row_shr:2 row_mask:0xf bank_mask:0xf
	v_mov_b32_dpp v134, v58 row_shr:1 row_mask:0xf bank_mask:0xf
	v_mov_b32_dpp v138, v58 row_shr:2 row_mask:0xf bank_mask:0xf
	v_mov_b32_dpp v135, v59 row_shr:1 row_mask:0xf bank_mask:0xf
	v_mov_b32_dpp v139, v59 row_shr:2 row_mask:0xf bank_mask:0xf
	v_rcp_f32_e32 v128, v128
	v_rcp_f32_e32 v129, v129
	v_rcp_f32_e32 v130, v130
	v_rcp_f32_e32 v131, v131
	v_pk_mul_f32 v[132:133], v[180:181], v[132:133]
	v_pk_mul_f32 v[134:135], v[182:183], v[134:135]
	v_pk_mul_f32 v[128:129], v[48:49], v[128:129]
	v_pk_mul_f32 v[130:131], v[50:51], v[130:131]
	v_pk_fma_f32 v[132:133], v[184:185], v[56:57], v[132:133]
	v_pk_fma_f32 v[134:135], v[186:187], v[58:59], v[134:135]
	v_pk_mul_f32 v[52:53], v[52:53], v[128:129]
	v_pk_mul_f32 v[54:55], v[54:55], v[130:131]
	v_pk_fma_f32 v[132:133], v[176:177], v[136:137], v[132:133]
	v_pk_fma_f32 v[134:135], v[178:179], v[138:139], v[134:135]
	v_cvt_pk_bf16_f32 v208, v52, v53
	v_cvt_pk_bf16_f32 v209, v54, v55
	v_pk_mul_f32 v[132:133], v[52:53], v[132:133]
	v_pk_mul_f32 v[134:135], v[54:55], v[134:135]
	v_cmp_gt_u32_e32 vcc, 2, v241
	s_add_u32 s100, s60, 0x2000
	s_addc_u32 s101, s61, 0
	s_nop 2
	s_and_saveexec_b64 s[4:5], vcc
	global_store_dwordx2 v211, v[208:209], s[100:101]
	s_mov_b64 exec, s[4:5]
	v_cvt_pk_bf16_f32 v198, v132, v133
	v_cvt_pk_bf16_f32 v199, v134, v135
	v_pk_mul_f32 v[128:129], v[16:17], s[42:43] op_sel_hi:[1,0]
	v_pk_mul_f32 v[130:131], v[18:19], s[42:43] op_sel_hi:[1,0]
	v_pk_mul_f32 v[40:41], v[44:45], v[40:41]
	v_pk_mul_f32 v[42:43], v[46:47], v[42:43]
	v_exp_f32_e32 v128, v128
	v_exp_f32_e32 v129, v129
	v_exp_f32_e32 v130, v130
	v_exp_f32_e32 v131, v131
	v_mov_b32_dpp v132, v56 row_ror:1 row_mask:0xf bank_mask:0xf
	v_mov_b32_dpp v136, v56 row_ror:2 row_mask:0xf bank_mask:0xf
	v_mov_b32_dpp v133, v57 row_ror:1 row_mask:0xf bank_mask:0xf
	v_mov_b32_dpp v137, v57 row_ror:2 row_mask:0xf bank_mask:0xf
	v_mov_b32_dpp v134, v58 row_ror:1 row_mask:0xf bank_mask:0xf
	v_mov_b32_dpp v138, v58 row_ror:2 row_mask:0xf bank_mask:0xf
	v_mov_b32_dpp v135, v59 row_ror:1 row_mask:0xf bank_mask:0xf
	v_mov_b32_dpp v139, v59 row_ror:2 row_mask:0xf bank_mask:0xf
	v_pk_add_f32 v[128:129], v[128:129], s[42:43] op_sel:[0,1] op_sel_hi:[1,1]
	v_pk_add_f32 v[130:131], v[130:131], s[42:43] op_sel:[0,1] op_sel_hi:[1,1]
	v_mov_b32_dpp v132, v40 row_shr:1 row_mask:0xf bank_mask:0xf
	v_mov_b32_dpp v136, v40 row_shr:2 row_mask:0xf bank_mask:0xf
	v_mov_b32_dpp v133, v41 row_shr:1 row_mask:0xf bank_mask:0xf
	v_mov_b32_dpp v137, v41 row_shr:2 row_mask:0xf bank_mask:0xf
	v_mov_b32_dpp v134, v42 row_shr:1 row_mask:0xf bank_mask:0xf
	v_mov_b32_dpp v138, v42 row_shr:2 row_mask:0xf bank_mask:0xf
	v_mov_b32_dpp v135, v43 row_shr:1 row_mask:0xf bank_mask:0xf
	v_mov_b32_dpp v139, v43 row_shr:2 row_mask:0xf bank_mask:0xf
	v_rcp_f32_e32 v128, v128
	v_rcp_f32_e32 v129, v129
	v_rcp_f32_e32 v130, v130
	v_rcp_f32_e32 v131, v131
	v_pk_mul_f32 v[132:133], v[180:181], v[132:133]
	v_pk_mul_f32 v[134:135], v[182:183], v[134:135]
	v_pk_mul_f32 v[128:129], v[16:17], v[128:129]
	v_pk_mul_f32 v[130:131], v[18:19], v[130:131]
	v_pk_fma_f32 v[132:133], v[184:185], v[40:41], v[132:133]
	v_pk_fma_f32 v[134:135], v[186:187], v[42:43], v[134:135]
	v_pk_mul_f32 v[20:21], v[20:21], v[128:129]
	v_pk_mul_f32 v[22:23], v[22:23], v[130:131]
	v_pk_fma_f32 v[132:133], v[176:177], v[136:137], v[132:133]
	v_pk_fma_f32 v[134:135], v[178:179], v[138:139], v[134:135]
	v_pk_mul_f32 v[132:133], v[20:21], v[132:133]
	v_pk_mul_f32 v[134:135], v[22:23], v[134:135]
	v_cvt_pk_bf16_f32 v200, v132, v133
	v_cvt_pk_bf16_f32 v201, v134, v135
	v_pk_mul_f32 v[128:129], v[8:9], s[42:43] op_sel_hi:[1,0]
	v_pk_mul_f32 v[130:131], v[10:11], s[42:43] op_sel_hi:[1,0]
	v_pk_mul_f32 v[32:33], v[36:37], v[32:33]
	v_pk_mul_f32 v[34:35], v[38:39], v[34:35]
	v_exp_f32_e32 v128, v128
	v_exp_f32_e32 v129, v129
	v_exp_f32_e32 v130, v130
	v_exp_f32_e32 v131, v131
	v_mov_b32_dpp v132, v40 row_ror:1 row_mask:0xf bank_mask:0xf
	v_mov_b32_dpp v136, v40 row_ror:2 row_mask:0xf bank_mask:0xf
	v_mov_b32_dpp v133, v41 row_ror:1 row_mask:0xf bank_mask:0xf
; __device__ __forceinline__ float siluf_(float x) { return x * sigmoidf_(x); }
; __device__ __forceinline__ u32x2 pk4(f32x4 v) { u32x2 r; r.x = pk_bf16(v[0], v[1]); r.y = pk_bf16(v[2], v[3]); return r; }
; template <int CTRL> __device__ __forceinline__ float dppf(float old, float v) { return __int_as_float(__builtin_amdgcn_update_dpp(__float_as_int(old), __float_as_int(v), CTRL, 0xf, 0xf, false)); }
;     __device__ __forceinline__ void operator()(const f32x4 (&acc)[2][2][4][2], const Unit& u, int wr, int wc, int fr, int fq) const {
;         if (u.kind <= 2) {
;             const int chw = (u.pn & 15) * 64 + wc * 16, ch = chw + pf(fq) * 4;
;             const int rowb = u.pm * 256 + wr * 64 + fr;
;             if (u.kind == 0) {
;                 const f32x4 w0 = *(const f32x4*)(convw + ch), w1 = *(const f32x4*)(convw + 1024 + ch), w2 = *(const f32x4*)(convw + 2048 + ch);
; #pragma unroll
;                 for (int ai = 0; ai < 2; ++ai) {
;                     const int blk = u.pm * 4 + ai * 2 + wr;
;                     f32x4 pprev = (f32x4){0.f, 0.f, 0.f, 0.f}; u32x2 hv[4];
; #pragma unroll
;                     for (int m = 0; m < 4; ++m) {
;                         const f32x4 Bv = acc[ai][0][m][0], Cv = acc[ai][0][m][1], Xv = acc[ai][1][m][0], Zv = acc[ai][1][m][1];
;                         const f32x4 p = Cv * Xv; f32x4 ga, p1, p2;
; #pragma unroll
;                         for (int j = 0; j < 4; ++j) {
;                             ga[j] = siluf_(Zv[j]) * Bv[j];
;                             const float r1 = (m > 0) ? dppf<0x121>(0.f, pprev[j]) : 0.f, r2 = (m > 0) ? dppf<0x122>(0.f, pprev[j]) : 0.f;
;                             p1[j] = dppf<0x111>(r1, p[j]); p2[j] = dppf<0x112>(r2, p[j]);
;                         }
;                         const f32x4 cv = w2 * p + w1 * p1 + w0 * p2;
;                         hv[m] = pk4(ga * cv);
;                         if (m == 3 && fr >= 14) *(u32x2*)(PAT + (size_t)(blk * 2 + (fr - 14)) * 1024 + ch) = pk4(p);
;                         if (m == 0 && fr < 2) *(u32x2*)(GAH + (size_t)(blk * 2 + fr) * 1024 + ch) = pk4(ga);
;                         pprev = p;
;                     }
; #pragma unroll
;                     for (int pr = 0; pr < 2; ++pr) store_pair16(HA + (size_t)(rowb + ai * 128 + pr * 32) * 1024 + chw, hv[2 * pr], hv[2 * pr + 1], fq);
;                 }
	v_mov_b32_dpp v137, v41 row_ror:2 row_mask:0xf bank_mask:0xf
	v_mov_b32_dpp v134, v42 row_ror:1 row_mask:0xf bank_mask:0xf
	v_mov_b32_dpp v138, v42 row_ror:2 row_mask:0xf bank_mask:0xf
	v_mov_b32_dpp v135, v43 row_ror:1 row_mask:0xf bank_mask:0xf
	v_mov_b32_dpp v139, v43 row_ror:2 row_mask:0xf bank_mask:0xf
	v_pk_add_f32 v[128:129], v[128:129], s[42:43] op_sel:[0,1] op_sel_hi:[1,1]
	v_pk_add_f32 v[130:131], v[130:131], s[42:43] op_sel:[0,1] op_sel_hi:[1,1]
	v_mov_b32_dpp v132, v32 row_shr:1 row_mask:0xf bank_mask:0xf
	v_mov_b32_dpp v136, v32 row_shr:2 row_mask:0xf bank_mask:0xf
	v_mov_b32_dpp v133, v33 row_shr:1 row_mask:0xf bank_mask:0xf
	v_mov_b32_dpp v137, v33 row_shr:2 row_mask:0xf bank_mask:0xf
	v_mov_b32_dpp v134, v34 row_shr:1 row_mask:0xf bank_mask:0xf
	v_mov_b32_dpp v138, v34 row_shr:2 row_mask:0xf bank_mask:0xf
	v_mov_b32_dpp v135, v35 row_shr:1 row_mask:0xf bank_mask:0xf
	v_mov_b32_dpp v139, v35 row_shr:2 row_mask:0xf bank_mask:0xf
	v_rcp_f32_e32 v128, v128
	v_rcp_f32_e32 v129, v129
	v_rcp_f32_e32 v130, v130
	v_rcp_f32_e32 v131, v131
	v_pk_mul_f32 v[132:133], v[180:181], v[132:133]
	v_pk_mul_f32 v[134:135], v[182:183], v[134:135]
	v_pk_mul_f32 v[128:129], v[8:9], v[128:129]
	v_pk_mul_f32 v[130:131], v[10:11], v[130:131]
	v_pk_fma_f32 v[132:133], v[184:185], v[32:33], v[132:133]
	v_pk_fma_f32 v[134:135], v[186:187], v[34:35], v[134:135]
	v_pk_mul_f32 v[12:13], v[12:13], v[128:129]
	v_pk_mul_f32 v[14:15], v[14:15], v[130:131]
	v_pk_fma_f32 v[132:133], v[176:177], v[136:137], v[132:133]
	v_pk_fma_f32 v[134:135], v[178:179], v[138:139], v[134:135]
	v_pk_mul_f32 v[132:133], v[12:13], v[132:133]
	v_pk_mul_f32 v[134:135], v[14:15], v[134:135]
	v_cvt_pk_bf16_f32 v202, v132, v133
	v_cvt_pk_bf16_f32 v203, v134, v135
	v_pk_mul_f32 v[128:129], v[0:1], s[42:43] op_sel_hi:[1,0]
	v_pk_mul_f32 v[130:131], v[2:3], s[42:43] op_sel_hi:[1,0]
	v_pk_mul_f32 v[24:25], v[28:29], v[24:25]
	v_pk_mul_f32 v[26:27], v[30:31], v[26:27]
	v_exp_f32_e32 v128, v128
	v_exp_f32_e32 v129, v129
	v_exp_f32_e32 v130, v130
	v_exp_f32_e32 v131, v131
	v_mov_b32_dpp v132, v32 row_ror:1 row_mask:0xf bank_mask:0xf
	v_mov_b32_dpp v136, v32 row_ror:2 row_mask:0xf bank_mask:0xf
	v_mov_b32_dpp v133, v33 row_ror:1 row_mask:0xf bank_mask:0xf
	v_mov_b32_dpp v137, v33 row_ror:2 row_mask:0xf bank_mask:0xf
	v_mov_b32_dpp v134, v34 row_ror:1 row_mask:0xf bank_mask:0xf
	v_mov_b32_dpp v138, v34 row_ror:2 row_mask:0xf bank_mask:0xf
	v_mov_b32_dpp v135, v35 row_ror:1 row_mask:0xf bank_mask:0xf
	v_mov_b32_dpp v139, v35 row_ror:2 row_mask:0xf bank_mask:0xf
	v_pk_add_f32 v[128:129], v[128:129], s[42:43] op_sel:[0,1] op_sel_hi:[1,1]
	v_pk_add_f32 v[130:131], v[130:131], s[42:43] op_sel:[0,1] op_sel_hi:[1,1]
	v_mov_b32_dpp v132, v24 row_shr:1 row_mask:0xf bank_mask:0xf
	v_mov_b32_dpp v136, v24 row_shr:2 row_mask:0xf bank_mask:0xf
	v_mov_b32_dpp v133, v25 row_shr:1 row_mask:0xf bank_mask:0xf
	v_mov_b32_dpp v137, v25 row_shr:2 row_mask:0xf bank_mask:0xf
	v_mov_b32_dpp v134, v26 row_shr:1 row_mask:0xf bank_mask:0xf
	v_mov_b32_dpp v138, v26 row_shr:2 row_mask:0xf bank_mask:0xf
	v_mov_b32_dpp v135, v27 row_shr:1 row_mask:0xf bank_mask:0xf
	v_mov_b32_dpp v139, v27 row_shr:2 row_mask:0xf bank_mask:0xf
	v_rcp_f32_e32 v128, v128
	v_rcp_f32_e32 v129, v129
	v_rcp_f32_e32 v130, v130
	v_rcp_f32_e32 v131, v131
	v_pk_mul_f32 v[132:133], v[180:181], v[132:133]
	v_pk_mul_f32 v[134:135], v[182:183], v[134:135]
	v_pk_mul_f32 v[128:129], v[0:1], v[128:129]
	v_pk_mul_f32 v[130:131], v[2:3], v[130:131]
	v_pk_fma_f32 v[132:133], v[184:185], v[24:25], v[132:133]
	v_pk_fma_f32 v[134:135], v[186:187], v[26:27], v[134:135]
	v_pk_mul_f32 v[4:5], v[4:5], v[128:129]
	v_pk_mul_f32 v[6:7], v[6:7], v[130:131]
	v_pk_fma_f32 v[132:133], v[176:177], v[136:137], v[132:133]
	v_pk_fma_f32 v[134:135], v[178:179], v[138:139], v[134:135]
	v_cvt_pk_bf16_f32 v206, v24, v25
	v_cvt_pk_bf16_f32 v207, v26, v27
	v_pk_mul_f32 v[132:133], v[4:5], v[132:133]
	v_pk_mul_f32 v[134:135], v[6:7], v[134:135]
	v_cmp_lt_u32_e32 vcc, 13, v241
	s_sub_u32 s100, s58, 0x5000
	s_subb_u32 s101, s59, 0
	s_nop 2
	s_and_saveexec_b64 s[4:5], vcc
	global_store_dwordx2 v211, v[206:207], s[100:101]
	s_mov_b64 exec, s[4:5]
	v_cvt_pk_bf16_f32 v204, v132, v133
	v_cvt_pk_bf16_f32 v205, v134, v135
	s_add_u32 s100, s98, 0x40000
	s_addc_u32 s101, s99, 0
	v_permlane32_swap_b32_e32 v198, v200
	v_permlane32_swap_b32_e32 v199, v201
	global_store_dwordx4 v212, v[198:201], s[100:101]
	s_add_u32 s100, s98, 0x50000
	s_addc_u32 s101, s99, 0
	v_permlane32_swap_b32_e32 v202, v204
	v_permlane32_swap_b32_e32 v203, v205
	global_store_dwordx4 v212, v[202:205], s[100:101]
	s_branch .LBB0_287

; #define GP_WAIT_V(n) asm volatile("s_waitcnt vmcnt(" #n ")" ::: "memory")
; #define GP_BAR __builtin_amdgcn_s_barrier()
; template <class Epi, class Sched>
; __device__ __forceinline__ void gemm_phase(LAS unsigned char* lds, const int lda, const int ldb, const int K, const Sched& S, const Epi& E, const int widx) {
;     int tid_ = tid_of(widx); asm volatile("" : "+v"(tid_));
;     const int tid = tid_, wid = __builtin_amdgcn_readfirstlane(tid >> 6), lane = tid & 63, wr = wid >> 2, wc = wid & 3, fr = lane & 15, fq = lane >> 4;
;     const int nt = K / BK;
;     unsigned voffA[2], voffB[2];
; #pragma unroll
;     for (int i = 0; i < 2; ++i) { int R, C; stage_rc(tid * 16 + i * 8192, R, C); voffA[i] = (unsigned)(R * lda + C) * 2u; voffB[i] = (unsigned)(R * ldb + C) * 2u; }
;     const size_t kstep = (size_t)(BK * 2);
;     const size_t hstepA = (size_t)HALF * lda * 2, hstepB = (size_t)HALF * ldb * 2;
;     const unsigned ldsw = (unsigned)wid * 1024u;
;     const int aoff = lds_byte(wr * 64 + fr, fq * 8), boff = lds_byte(wc * 32 + fr, fq * 8);
;     ...
;     Unit cur, nxt; int ui = 0;
;     if (!S.next(0, cur)) return;
;     f32x4 acc[2][2][4][2];
; #pragma unroll
;     for (int a = 0; a < 2; ++a)
; #pragma unroll
;         for (int b = 0; b < 2; ++b)
; #pragma unroll
;             for (int m = 0; m < 4; ++m)
; #pragma unroll
;                 for (int n = 0; n < 2; ++n) acc[a][b][m][n] = (f32x4){0.f, 0.f, 0.f, 0.f};
;     bf16x8 At[4][2], B0[2][2], B1[2][2];
;     const char* cA = cur.A; const char* cB = cur.B;
;     GP_STAGE(GP_SB(0, 0), cB, voffB); GP_STAGE(GP_SB(0, 1), cB + hstepB, voffB); GP_STAGE(GP_SA(0, 0), cA, voffA); GP_STAGE(GP_SA(0, 1), cA + hstepA, voffA);
;     if (wr == 1) GP_BAR;
;     GP_WAIT_V(2); GP_BAR;
;     GP_STAGE(GP_SB(1, 0), cB + kstep, voffB); GP_STAGE(GP_SA(1, 0), cA + kstep, voffA); GP_STAGE(GP_SB(1, 1), cB + hstepB + kstep, voffB);
;     GP_WAIT_V(6); GP_BAR;
; __global__ void __launch_bounds__(512, 2) fwd_megakernel(Params p) {
;     ...
;     asm volatile("s_waitcnt vmcnt(0) lgkmcnt(0)" ::: "memory"); __syncthreads();
;     __builtin_amdgcn_fence(__ATOMIC_ACQUIRE, "agent"); asm volatile("s_waitcnt vmcnt(0)" ::: "memory"); __syncthreads();
;     { SchedAttn S{(const char*)Q, (const char*)VT, (size_t)1024 * 256 * 2, (size_t)256 * 256 * 2, G, bx}; EpiPV E{SZX, U  , RSUM}; gemm_phase(lds, 1024, 256, 256, S, E, widx); }
.LBB0_385:
.LBB0_458:
	s_waitcnt vmcnt(0) lgkmcnt(0)
	s_barrier
	s_waitcnt vmcnt(0) lgkmcnt(0)
	s_barrier
	buffer_inv sc0
	s_waitcnt vmcnt(0)
	s_barrier
	v_mbcnt_lo_u32_b32 v0, -1, 0
	v_mbcnt_hi_u32_b32 v0, -1, v0
	v_readlane_b32 s66, v255, 4
	v_add_u32_e32 v8, s87, v0
	s_and_b64 vcc, exec, s[0:1]
	v_readfirstlane_b32 s5, v8
	v_readlane_b32 s67, v255, 5
	s_cbranch_vccnz .LBB0_472
	v_lshlrev_b32_e32 v0, 4, v8
	v_add_u32_e32 v1, 0x2000, v0
	v_ashrrev_i32_e32 v2, 31, v1
	v_lshrrev_b32_e32 v2, 22, v2
	v_add_u32_e32 v2, v1, v2
	v_ashrrev_i32_e32 v2, 10, v2
	v_mul_i32_i24_e32 v4, 0x400, v2
	v_sub_u32_e32 v1, v1, v4
	v_lshrrev_b32_e32 v4, 4, v1
	v_bitop3_b32 v1, v4, v1, 32 bitop3:0x6c
	v_ashrrev_i32_e32 v4, 31, v1
	v_lshrrev_b32_e32 v4, 26, v4
	v_add_u32_e32 v4, v1, v4
	v_lshlrev_b32_e32 v3, 5, v2
	v_ashrrev_i32_e32 v5, 6, v4
	v_and_b32_e32 v4, 0xc0, v4
	v_lshlrev_b32_e32 v2, 3, v2
	v_sub_u32_e32 v1, v1, v4
	v_mov_b32_e32 v4, 1
	v_and_b32_e32 v2, -16, v2
	v_and_b32_e32 v3, 32, v3
	v_ashrrev_i16_sdwa v1, v4, sext(v1) dst_sel:DWORD dst_unused:UNUSED_PAD src0_sel:DWORD src1_sel:BYTE_0
	v_add_u32_e32 v2, v5, v2
	v_add_u32_sdwa v1, v3, sext(v1) dst_sel:DWORD dst_unused:UNUSED_PAD src0_sel:DWORD src1_sel:WORD_0
	v_lshlrev_b32_e32 v3, 9, v2
	v_lshl_add_u32 v128, v1, 1, v3
	v_bfe_i32 v3, v8, 27, 1
	v_lshrrev_b32_e32 v3, 22, v3
	v_add_u32_e32 v3, v0, v3
	v_and_b32_e32 v3, 0xfffffc00, v3
	v_sub_u32_e32 v0, v0, v3
	v_lshrrev_b32_e32 v3, 4, v0
	v_ashrrev_i32_e32 v1, 31, v8
	v_bitop3_b32 v0, v3, v0, 32 bitop3:0x6c
	v_lshrrev_b32_e32 v1, 26, v1
	v_ashrrev_i32_e32 v3, 31, v0
	v_add_u32_e32 v1, v8, v1
	v_lshrrev_b32_e32 v3, 26, v3
	s_movk_i32 s7, 0x600
	v_ashrrev_i32_e32 v1, 6, v1
	v_add_u32_e32 v3, v0, v3
	v_mad_u64_u32 v[130:131], s[8:9], v2, s7, v[128:129]
	v_lshlrev_b32_e32 v2, 5, v1
	v_ashrrev_i32_e32 v5, 6, v3
	v_and_b32_e32 v3, 0xc0, v3
	v_lshlrev_b32_e32 v1, 3, v1
	v_sub_u32_e32 v0, v0, v3
	v_and_b32_e32 v1, -16, v1
	v_and_b32_e32 v2, 32, v2
	v_ashrrev_i16_sdwa v0, v4, sext(v0) dst_sel:DWORD dst_unused:UNUSED_PAD src0_sel:DWORD src1_sel:BYTE_0
	v_add_u32_e32 v1, v5, v1
	v_add_u32_sdwa v0, v2, sext(v0) dst_sel:DWORD dst_unused:UNUSED_PAD src0_sel:DWORD src1_sel:WORD_0
	v_lshlrev_b32_e32 v2, 9, v1
	v_lshl_add_u32 v132, v0, 1, v2
	s_ashr_i32 s28, s2, 2
	s_ashr_i32 s10, s5, 6
	v_mad_u64_u32 v[134:135], s[8:9], v1, s7, v[132:133]
	s_ashr_i32 s29, s28, 31
	s_ashr_i32 s6, s5, 8
	s_lshl_b32 s4, s10, 10
	s_and_b32 s78, s2, 3
	s_lshl_b64 s[8:9], s[28:29], 19
	s_add_u32 s7, s46, s8
	s_addc_u32 s8, s47, s9
	s_lshl_b32 s9, s78, 9
	s_add_u32 s60, s7, s9
	s_addc_u32 s61, s8, 0
	s_ashr_i32 s8, s2, 7
	s_ashr_i32 s9, s8, 31
	s_lshl_b64 s[8:9], s[8:9], 19
	s_add_u32 s7, s38, s8
	s_addc_u32 s8, s39, s9
	s_lshl_b32 s9, s78, 17
	s_add_u32 s62, s7, s9
	s_addc_u32 s63, s8, 0
	s_add_i32 s12, s4, 0
	s_add_i32 m0, s12, 0x10000
	v_mov_b32_e32 v133, 0
	global_load_lds_dwordx4 v132, s[62:63]
	s_add_i32 m0, s12, 0x12000
	s_add_u32 s8, s62, 0x10000
	global_load_lds_dwordx4 v128, s[62:63]
	s_addc_u32 s9, s63, 0
	s_add_i32 m0, s12, 0x14000
	s_add_i32 s13, s12, 0x2000
	global_load_lds_dwordx4 v132, s[8:9]
	s_add_i32 m0, s12, 0x16000
	v_mov_b32_e32 v129, v133
	global_load_lds_dwordx4 v128, s[8:9]
	s_mov_b32 m0, s12
	s_add_u32 s8, s60, 0x40000
	global_load_lds_dwordx4 v134, s[60:61]
	s_mov_b32 m0, s13
	s_addc_u32 s9, s61, 0
	s_add_i32 s33, s12, 0x4000
	global_load_lds_dwordx4 v130, s[60:61]
	s_mov_b32 m0, s33
	s_add_i32 s34, s12, 0x6000
	global_load_lds_dwordx4 v134, s[8:9]
	s_mov_b32 m0, s34
	v_mov_b32_e32 v135, v133
	global_load_lds_dwordx4 v130, s[8:9]
	v_mov_b32_e32 v131, v133
	s_cmp_eq_u32 s6, 1
	s_movk_i32 s35, 0x2000
	s_mov_b32 s7, 0
	v_lshl_add_u64 v[6:7], s[62:63], 0, v[132:133]
	v_lshl_add_u64 v[4:5], s[62:63], 0, v[128:129]
	v_lshl_add_u64 v[0:1], s[60:61], 0, v[134:135]
	s_cselect_b64 s[8:9], -1, 0
	s_cmp_lg_u32 s6, 1
	v_lshl_add_u64 v[2:3], s[60:61], 0, v[130:131]
	s_cbranch_scc1 .LBB0_461
	s_barrier

; #define GP_STAGE(bufoff, gbase, voff) do { _Pragma("unroll") for (int _i = 0; _i < 2; ++_i) \
;         __builtin_amdgcn_global_load_lds((const unsigned*)((const char*)(gbase) + (voff)[_i]), (LAS unsigned*)(lds + (bufoff) + ldsw + _i * 8192), 16, 0, 0); } while (0)
; #define GP_LDA(dst, b, h) do { _Pragma("unroll") for (int m = 0; m < 4; ++m) _Pragma("unroll") for (int k = 0; k < 2; ++k) dst[m][k] = *(const LAS bf16x8*)(lds + GP_SA(b, h) + aoff + m * 2048 + k * 1024); } while (0)
; #define GP_LDB(dst, b, h) do { _Pragma("unroll") for (int n = 0; n < 2; ++n) _Pragma("unroll") for (int k = 0; k < 2; ++k) dst[n][k] = *(const LAS bf16x8*)(lds + GP_SB(b, h) + boff + n * 2048 + k * 1024); } while (0)
; #define GP_WAIT_V(n) asm volatile("s_waitcnt vmcnt(" #n ")" ::: "memory")
; #define GP_WAIT_L(n) asm volatile("s_waitcnt lgkmcnt(" #n ")" ::: "memory")
; template <class Epi, class Sched>
; __device__ __forceinline__ void gemm_phase(LAS unsigned char* lds, const int lda, const int ldb, const int K, const Sched& S, const Epi& E, const int widx) {
;     ...
;         for (int t = 0; t < nt; t += 2) {
;             const bool last = (t == nt - 2);
;             const char* a1 = cA + (size_t)(t + 1) * kstep;
;             const char* a2 = last ? nA : cA + (size_t)(t + 2) * kstep; const char* b2 = last ? nB : cB + (size_t)(t + 2) * kstep;
;             const char* a3 = a2 + kstep; const char* b3 = b2 + kstep;
;             GP_LDB(B0, 0, 0); GP_LDB(B1, 0, 1); GP_SCHED; GP_LDA(At, 0, 0); GP_STAGE(GP_SA(1, 1), a1 + hstepA, voffA);
;             GP_WAIT_V(8); GP_WAIT_L(0); GP_BAR; GP_MMA(0, 0, At, B0); GP_MMA(0, 1, At, B1); GP_BAR; GP_SCHED;
;             GP_LDA(At, 0, 1); GP_STAGE(GP_SB(0, 0), b2, voffB); GP_STAGE(GP_SB(0, 1), b2 + hstepB, voffB); GP_STAGE(GP_SA(0, 0), a2, voffA);
;             GP_WAIT_V(8); GP_WAIT_L(0); GP_BAR; GP_MMA(1, 0, At, B0); GP_MMA(1, 1, At, B1); GP_BAR; GP_SCHED;
;             GP_LDB(B0, 1, 0); GP_LDB(B1, 1, 1); GP_SCHED; GP_LDA(At, 1, 0); GP_STAGE(GP_SA(0, 1), a2 + hstepA, voffA);
;             GP_WAIT_V(8); GP_WAIT_L(0); GP_BAR; GP_MMA(0, 0, At, B0); GP_MMA(0, 1, At, B1); GP_BAR; GP_SCHED;
;             GP_LDA(At, 1, 1); GP_STAGE(GP_SB(1, 0), b3, voffB); GP_STAGE(GP_SB(1, 1), b3 + hstepB, voffB); GP_STAGE(GP_SA(1, 0), a3, voffA);
;             GP_WAIT_V(8); GP_WAIT_L(0); GP_BAR; GP_MMA(1, 0, At, B0); GP_MMA(1, 1, At, B1); GP_BAR; GP_SCHED;
.LBB0_545:
	v_add_u32_e32 v141, s73, v147
	ds_read_b128 v[142:145], v141
	ds_read_b128 v[152:155], v141 offset:1024
	ds_read_b128 v[156:159], v141 offset:2048
	ds_read_b128 v[160:163], v141 offset:3072
	v_add_u32_e32 v141, s74, v147
	ds_read_b128 v[166:169], v141
	ds_read_b128 v[170:173], v141 offset:1024
	ds_read_b128 v[174:177], v141 offset:2048
	ds_read_b128 v[178:181], v141 offset:3072
	s_add_u32 s34, s28, 0xfffc0080
	s_addc_u32 s35, s29, -1
	s_cmp_eq_u32 s41, 12
	s_cselect_b32 s35, s59, s35
	s_cselect_b32 s34, s58, s34
	s_cselect_b32 s67, s61, s39
	s_cselect_b32 s66, s60, s4
	s_add_i32 m0, s13, 0xc000
	ds_read_b128 v[182:185], v151
	ds_read_b128 v[186:189], v151 offset:1024
	ds_read_b128 v[190:193], v151 offset:2048
	ds_read_b128 v[194:197], v151 offset:3072
	ds_read_b128 v[198:201], v151 offset:4096
	ds_read_b128 v[202:205], v151 offset:5120
	ds_read_b128 v[206:209], v151 offset:6144
	ds_read_b128 v[210:213], v151 offset:7168
	global_load_lds_dwordx4 v136, s[28:29]
	s_add_i32 m0, s13, 0xe000
	s_nop 0
	global_load_lds_dwordx4 v138, s[28:29]
	s_waitcnt vmcnt(8)
	s_waitcnt lgkmcnt(0)
	s_barrier
	s_setprio 1
	s_waitcnt lgkmcnt(0)
	v_mfma_f32_16x16x32_bf16 v[124:127], v[142:145], v[182:185], v[124:127]
	v_mfma_f32_16x16x32_bf16 v[120:123], v[156:159], v[182:185], v[120:123]
	v_mfma_f32_16x16x32_bf16 v[116:119], v[142:145], v[190:193], v[116:119]
	v_mfma_f32_16x16x32_bf16 v[112:115], v[156:159], v[190:193], v[112:115]
	v_mfma_f32_16x16x32_bf16 v[108:111], v[142:145], v[198:201], v[108:111]
	v_mfma_f32_16x16x32_bf16 v[104:107], v[156:159], v[198:201], v[104:107]
	v_mfma_f32_16x16x32_bf16 v[100:103], v[142:145], v[206:209], v[100:103]
	v_mfma_f32_16x16x32_bf16 v[96:99], v[156:159], v[206:209], v[96:99]
	v_mfma_f32_16x16x32_bf16 v[124:127], v[152:155], v[186:189], v[124:127]
	v_mfma_f32_16x16x32_bf16 v[120:123], v[160:163], v[186:189], v[120:123]
	v_mfma_f32_16x16x32_bf16 v[116:119], v[152:155], v[194:197], v[116:119]
	v_mfma_f32_16x16x32_bf16 v[112:115], v[160:163], v[194:197], v[112:115]
	v_mfma_f32_16x16x32_bf16 v[108:111], v[152:155], v[202:205], v[108:111]
	v_mfma_f32_16x16x32_bf16 v[104:107], v[160:163], v[202:205], v[104:107]
	v_mfma_f32_16x16x32_bf16 v[100:103], v[152:155], v[210:213], v[100:103]
	v_mfma_f32_16x16x32_bf16 v[96:99], v[160:163], v[210:213], v[96:99]
	s_setprio 0
	s_setprio 1
	v_mfma_f32_16x16x32_bf16 v[92:95], v[166:169], v[182:185], v[92:95]
	v_mfma_f32_16x16x32_bf16 v[88:91], v[174:177], v[182:185], v[88:91]
	v_mfma_f32_16x16x32_bf16 v[84:87], v[166:169], v[190:193], v[84:87]
	v_mfma_f32_16x16x32_bf16 v[80:83], v[174:177], v[190:193], v[80:83]
	v_mfma_f32_16x16x32_bf16 v[76:79], v[166:169], v[198:201], v[76:79]
	v_mfma_f32_16x16x32_bf16 v[72:75], v[174:177], v[198:201], v[72:75]
	v_mfma_f32_16x16x32_bf16 v[68:71], v[166:169], v[206:209], v[68:71]
	v_mfma_f32_16x16x32_bf16 v[64:67], v[174:177], v[206:209], v[64:67]
	v_mfma_f32_16x16x32_bf16 v[92:95], v[170:173], v[186:189], v[92:95]
	v_mfma_f32_16x16x32_bf16 v[88:91], v[178:181], v[186:189], v[88:91]
	v_mfma_f32_16x16x32_bf16 v[84:87], v[170:173], v[194:197], v[84:87]
	v_mfma_f32_16x16x32_bf16 v[80:83], v[178:181], v[194:197], v[80:83]
	v_mfma_f32_16x16x32_bf16 v[76:79], v[170:173], v[202:205], v[76:79]
	v_mfma_f32_16x16x32_bf16 v[72:75], v[178:181], v[202:205], v[72:75]
	v_mfma_f32_16x16x32_bf16 v[68:71], v[170:173], v[210:213], v[68:71]
	v_mfma_f32_16x16x32_bf16 v[64:67], v[178:181], v[210:213], v[64:67]
	s_setprio 0
	s_barrier
	s_add_i32 s55, s73, s12
	s_mov_b32 m0, s55
	ds_read_b128 v[182:185], v151 offset:16384
	ds_read_b128 v[186:189], v151 offset:17408
	ds_read_b128 v[190:193], v151 offset:18432
	ds_read_b128 v[194:197], v151 offset:19456
	ds_read_b128 v[198:201], v151 offset:20480
	ds_read_b128 v[202:205], v151 offset:21504
	ds_read_b128 v[206:209], v151 offset:22528
	ds_read_b128 v[210:213], v151 offset:23552
	global_load_lds_dwordx4 v128, s[66:67]
	s_add_i32 m0, s55, 0x2000
	s_add_u32 s78, s66, 0x40000
	s_addc_u32 s79, s67, 0
	s_add_i32 s55, s74, s12
	global_load_lds_dwordx4 v130, s[66:67]
	s_mov_b32 m0, s55
	s_nop 0
	global_load_lds_dwordx4 v128, s[78:79]
	s_add_i32 m0, s55, 0x2000
	s_nop 0
	global_load_lds_dwordx4 v130, s[78:79]
	s_mov_b32 m0, s13
	s_nop 0
	global_load_lds_dwordx4 v128, s[34:35]
	s_mov_b32 m0, s33
	s_nop 0
	global_load_lds_dwordx4 v130, s[34:35]
	s_add_u32 s100, s34, 0x80
	s_addc_u32 s101, s35, 0
	s_waitcnt vmcnt(8)
	s_waitcnt lgkmcnt(0)
	s_barrier
	s_setprio 1
	s_waitcnt lgkmcnt(0)
	v_mfma_f32_16x16x32_bf16 v[60:63], v[142:145], v[182:185], v[60:63]
	v_mfma_f32_16x16x32_bf16 v[56:59], v[156:159], v[182:185], v[56:59]
	v_mfma_f32_16x16x32_bf16 v[52:55], v[142:145], v[190:193], v[52:55]
	v_mfma_f32_16x16x32_bf16 v[48:51], v[156:159], v[190:193], v[48:51]
	v_mfma_f32_16x16x32_bf16 v[44:47], v[142:145], v[198:201], v[44:47]
	v_mfma_f32_16x16x32_bf16 v[40:43], v[156:159], v[198:201], v[40:43]
	v_mfma_f32_16x16x32_bf16 v[36:39], v[142:145], v[206:209], v[36:39]
	v_mfma_f32_16x16x32_bf16 v[32:35], v[156:159], v[206:209], v[32:35]
	v_mfma_f32_16x16x32_bf16 v[60:63], v[152:155], v[186:189], v[60:63]
	v_mfma_f32_16x16x32_bf16 v[56:59], v[160:163], v[186:189], v[56:59]
	v_mfma_f32_16x16x32_bf16 v[52:55], v[152:155], v[194:197], v[52:55]
	v_mfma_f32_16x16x32_bf16 v[48:51], v[160:163], v[194:197], v[48:51]
	v_mfma_f32_16x16x32_bf16 v[44:47], v[152:155], v[202:205], v[44:47]
	v_mfma_f32_16x16x32_bf16 v[40:43], v[160:163], v[202:205], v[40:43]
	v_mfma_f32_16x16x32_bf16 v[36:39], v[152:155], v[210:213], v[36:39]
	v_mfma_f32_16x16x32_bf16 v[32:35], v[160:163], v[210:213], v[32:35]
	s_setprio 0
	s_setprio 1
	v_mfma_f32_16x16x32_bf16 v[28:31], v[166:169], v[182:185], v[28:31]
	v_mfma_f32_16x16x32_bf16 v[24:27], v[174:177], v[182:185], v[24:27]
	v_mfma_f32_16x16x32_bf16 v[20:23], v[166:169], v[190:193], v[20:23]
	v_mfma_f32_16x16x32_bf16 v[16:19], v[174:177], v[190:193], v[16:19]
	v_mfma_f32_16x16x32_bf16 v[12:15], v[166:169], v[198:201], v[12:15]
	v_mfma_f32_16x16x32_bf16 v[8:11], v[174:177], v[198:201], v[8:11]
	v_mfma_f32_16x16x32_bf16 v[4:7], v[166:169], v[206:209], v[4:7]
	v_mfma_f32_16x16x32_bf16 v[0:3], v[174:177], v[206:209], v[0:3]
	v_mfma_f32_16x16x32_bf16 v[28:31], v[170:173], v[186:189], v[28:31]
	v_mfma_f32_16x16x32_bf16 v[24:27], v[178:181], v[186:189], v[24:27]
	v_mfma_f32_16x16x32_bf16 v[20:23], v[170:173], v[194:197], v[20:23]
	v_mfma_f32_16x16x32_bf16 v[16:19], v[178:181], v[194:197], v[16:19]
	v_mfma_f32_16x16x32_bf16 v[12:15], v[170:173], v[202:205], v[12:15]
	v_mfma_f32_16x16x32_bf16 v[8:11], v[178:181], v[202:205], v[8:11]
	v_mfma_f32_16x16x32_bf16 v[4:7], v[170:173], v[210:213], v[4:7]
	v_mfma_f32_16x16x32_bf16 v[0:3], v[178:181], v[210:213], v[0:3]
	s_setprio 0
	s_barrier
; #define GP_STAGE(bufoff, gbase, voff) do { _Pragma("unroll") for (int _i = 0; _i < 2; ++_i) \
;         __builtin_amdgcn_global_load_lds((const unsigned*)((const char*)(gbase) + (voff)[_i]), (LAS unsigned*)(lds + (bufoff) + ldsw + _i * 8192), 16, 0, 0); } while (0)
; #define GP_LDA(dst, b, h) do { _Pragma("unroll") for (int m = 0; m < 4; ++m) _Pragma("unroll") for (int k = 0; k < 2; ++k) dst[m][k] = *(const LAS bf16x8*)(lds + GP_SA(b, h) + aoff + m * 2048 + k * 1024); } while (0)
; #define GP_LDB(dst, b, h) do { _Pragma("unroll") for (int n = 0; n < 2; ++n) _Pragma("unroll") for (int k = 0; k < 2; ++k) dst[n][k] = *(const LAS bf16x8*)(lds + GP_SB(b, h) + boff + n * 2048 + k * 1024); } while (0)
; #define GP_WAIT_V(n) asm volatile("s_waitcnt vmcnt(" #n ")" ::: "memory")
; #define GP_WAIT_L(n) asm volatile("s_waitcnt lgkmcnt(" #n ")" ::: "memory")
; template <class Epi, class Sched>
; __device__ __forceinline__ void gemm_phase(LAS unsigned char* lds, const int lda, const int ldb, const int K, const Sched& S, const Epi& E, const int widx) {
;     ...
;         for (int t = 0; t < nt; t += 2) {
;             const bool last = (t == nt - 2);
;             const char* a1 = cA + (size_t)(t + 1) * kstep;
;             const char* a2 = last ? nA : cA + (size_t)(t + 2) * kstep; const char* b2 = last ? nB : cB + (size_t)(t + 2) * kstep;
;             const char* a3 = a2 + kstep; const char* b3 = b2 + kstep;
;             GP_LDB(B0, 0, 0); GP_LDB(B1, 0, 1); GP_SCHED; GP_LDA(At, 0, 0); GP_STAGE(GP_SA(1, 1), a1 + hstepA, voffA);
;             GP_WAIT_V(8); GP_WAIT_L(0); GP_BAR; GP_MMA(0, 0, At, B0); GP_MMA(0, 1, At, B1); GP_BAR; GP_SCHED;
;             GP_LDA(At, 0, 1); GP_STAGE(GP_SB(0, 0), b2, voffB); GP_STAGE(GP_SB(0, 1), b2 + hstepB, voffB); GP_STAGE(GP_SA(0, 0), a2, voffA);
;             GP_WAIT_V(8); GP_WAIT_L(0); GP_BAR; GP_MMA(1, 0, At, B0); GP_MMA(1, 1, At, B1); GP_BAR; GP_SCHED;
;             GP_LDB(B0, 1, 0); GP_LDB(B1, 1, 1); GP_SCHED; GP_LDA(At, 1, 0); GP_STAGE(GP_SA(0, 1), a2 + hstepA, voffA);
;             GP_WAIT_V(8); GP_WAIT_L(0); GP_BAR; GP_MMA(0, 0, At, B0); GP_MMA(0, 1, At, B1); GP_BAR; GP_SCHED;
;             GP_LDA(At, 1, 1); GP_STAGE(GP_SB(1, 0), b3, voffB); GP_STAGE(GP_SB(1, 1), b3 + hstepB, voffB); GP_STAGE(GP_SA(1, 0), a3, voffA);
;             GP_WAIT_V(8); GP_WAIT_L(0); GP_BAR; GP_MMA(1, 0, At, B0); GP_MMA(1, 1, At, B1); GP_BAR; GP_SCHED;
	s_add_i32 s55, 0, 0x18000
	v_add_u32_e32 v141, s55, v147
	s_add_i32 s57, 0, 0x1c000
	ds_read_b128 v[142:145], v141
	ds_read_b128 v[152:155], v141 offset:1024
	ds_read_b128 v[156:159], v141 offset:2048
	ds_read_b128 v[160:163], v141 offset:3072
	v_add_u32_e32 v141, s57, v147
	ds_read_b128 v[166:169], v141
	ds_read_b128 v[170:173], v141 offset:1024
	ds_read_b128 v[174:177], v141 offset:2048
	ds_read_b128 v[178:181], v141 offset:3072
	s_add_u32 s34, s34, 0x40000
	s_addc_u32 s35, s35, 0
	s_mov_b32 m0, s65
	ds_read_b128 v[182:185], v151 offset:32768
	ds_read_b128 v[186:189], v151 offset:33792
	ds_read_b128 v[190:193], v151 offset:34816
	ds_read_b128 v[194:197], v151 offset:35840
	ds_read_b128 v[198:201], v151 offset:36864
	ds_read_b128 v[202:205], v151 offset:37888
	ds_read_b128 v[206:209], v151 offset:38912
	ds_read_b128 v[210:213], v151 offset:39936
	global_load_lds_dwordx4 v128, s[34:35]
	s_mov_b32 m0, s70
	s_nop 0
	global_load_lds_dwordx4 v130, s[34:35]
	s_waitcnt vmcnt(8)
	s_waitcnt lgkmcnt(0)
	s_barrier
	s_setprio 1
	s_waitcnt lgkmcnt(0)
	v_mfma_f32_16x16x32_bf16 v[124:127], v[142:145], v[182:185], v[124:127]
	v_mfma_f32_16x16x32_bf16 v[120:123], v[156:159], v[182:185], v[120:123]
	v_mfma_f32_16x16x32_bf16 v[116:119], v[142:145], v[190:193], v[116:119]
	v_mfma_f32_16x16x32_bf16 v[112:115], v[156:159], v[190:193], v[112:115]
	v_mfma_f32_16x16x32_bf16 v[108:111], v[142:145], v[198:201], v[108:111]
	v_mfma_f32_16x16x32_bf16 v[104:107], v[156:159], v[198:201], v[104:107]
	v_mfma_f32_16x16x32_bf16 v[100:103], v[142:145], v[206:209], v[100:103]
	v_mfma_f32_16x16x32_bf16 v[96:99], v[156:159], v[206:209], v[96:99]
	v_mfma_f32_16x16x32_bf16 v[124:127], v[152:155], v[186:189], v[124:127]
	v_mfma_f32_16x16x32_bf16 v[120:123], v[160:163], v[186:189], v[120:123]
	v_mfma_f32_16x16x32_bf16 v[116:119], v[152:155], v[194:197], v[116:119]
	v_mfma_f32_16x16x32_bf16 v[112:115], v[160:163], v[194:197], v[112:115]
	v_mfma_f32_16x16x32_bf16 v[108:111], v[152:155], v[202:205], v[108:111]
	v_mfma_f32_16x16x32_bf16 v[104:107], v[160:163], v[202:205], v[104:107]
	v_mfma_f32_16x16x32_bf16 v[100:103], v[152:155], v[210:213], v[100:103]
	v_mfma_f32_16x16x32_bf16 v[96:99], v[160:163], v[210:213], v[96:99]
	s_setprio 0
	s_setprio 1
	v_mfma_f32_16x16x32_bf16 v[92:95], v[166:169], v[182:185], v[92:95]
	v_mfma_f32_16x16x32_bf16 v[88:91], v[174:177], v[182:185], v[88:91]
	v_mfma_f32_16x16x32_bf16 v[84:87], v[166:169], v[190:193], v[84:87]
	v_mfma_f32_16x16x32_bf16 v[80:83], v[174:177], v[190:193], v[80:83]
	v_mfma_f32_16x16x32_bf16 v[76:79], v[166:169], v[198:201], v[76:79]
	v_mfma_f32_16x16x32_bf16 v[72:75], v[174:177], v[198:201], v[72:75]
	v_mfma_f32_16x16x32_bf16 v[68:71], v[166:169], v[206:209], v[68:71]
	v_mfma_f32_16x16x32_bf16 v[64:67], v[174:177], v[206:209], v[64:67]
	v_mfma_f32_16x16x32_bf16 v[92:95], v[170:173], v[186:189], v[92:95]
	v_mfma_f32_16x16x32_bf16 v[88:91], v[178:181], v[186:189], v[88:91]
	v_mfma_f32_16x16x32_bf16 v[84:87], v[170:173], v[194:197], v[84:87]
	v_mfma_f32_16x16x32_bf16 v[80:83], v[178:181], v[194:197], v[80:83]
	v_mfma_f32_16x16x32_bf16 v[76:79], v[170:173], v[202:205], v[76:79]
	v_mfma_f32_16x16x32_bf16 v[72:75], v[178:181], v[202:205], v[72:75]
	v_mfma_f32_16x16x32_bf16 v[68:71], v[170:173], v[210:213], v[68:71]
	v_mfma_f32_16x16x32_bf16 v[64:67], v[178:181], v[210:213], v[64:67]
	s_setprio 0
	s_barrier
	s_add_i32 s34, s55, s12
	s_add_u32 s98, s66, 0x80
	s_addc_u32 s99, s67, 0
	s_mov_b32 m0, s34
	ds_read_b128 v[182:185], v151 offset:49152
	ds_read_b128 v[186:189], v151 offset:50176
	ds_read_b128 v[190:193], v151 offset:51200
	ds_read_b128 v[194:197], v151 offset:52224
	ds_read_b128 v[198:201], v151 offset:53248
	ds_read_b128 v[202:205], v151 offset:54272
	ds_read_b128 v[206:209], v151 offset:55296
	ds_read_b128 v[210:213], v151 offset:56320
	global_load_lds_dwordx4 v128, s[98:99]
	s_add_i32 m0, s34, 0x2000
	s_add_u32 s34, s66, 0x40080
	s_addc_u32 s35, s67, 0
	s_add_i32 s55, s57, s12
	global_load_lds_dwordx4 v130, s[98:99]
	s_mov_b32 m0, s55
	s_nop 0
	global_load_lds_dwordx4 v128, s[34:35]
	s_add_i32 m0, s55, 0x2000
	s_nop 0
	global_load_lds_dwordx4 v130, s[34:35]
	s_mov_b32 m0, s71
	s_nop 0
	global_load_lds_dwordx4 v128, s[100:101]
	s_mov_b32 m0, s72
	s_nop 0
	global_load_lds_dwordx4 v130, s[100:101]
	s_waitcnt vmcnt(8)
	s_waitcnt lgkmcnt(0)
	s_barrier
	s_setprio 1
	s_waitcnt lgkmcnt(0)
	v_mfma_f32_16x16x32_bf16 v[60:63], v[142:145], v[182:185], v[60:63]
	v_mfma_f32_16x16x32_bf16 v[56:59], v[156:159], v[182:185], v[56:59]
	v_mfma_f32_16x16x32_bf16 v[52:55], v[142:145], v[190:193], v[52:55]
	v_mfma_f32_16x16x32_bf16 v[48:51], v[156:159], v[190:193], v[48:51]
	v_mfma_f32_16x16x32_bf16 v[44:47], v[142:145], v[198:201], v[44:47]
	v_mfma_f32_16x16x32_bf16 v[40:43], v[156:159], v[198:201], v[40:43]
	v_mfma_f32_16x16x32_bf16 v[36:39], v[142:145], v[206:209], v[36:39]
	v_mfma_f32_16x16x32_bf16 v[32:35], v[156:159], v[206:209], v[32:35]
	v_mfma_f32_16x16x32_bf16 v[60:63], v[152:155], v[186:189], v[60:63]
	v_mfma_f32_16x16x32_bf16 v[56:59], v[160:163], v[186:189], v[56:59]
	v_mfma_f32_16x16x32_bf16 v[52:55], v[152:155], v[194:197], v[52:55]
	v_mfma_f32_16x16x32_bf16 v[48:51], v[160:163], v[194:197], v[48:51]
	v_mfma_f32_16x16x32_bf16 v[44:47], v[152:155], v[202:205], v[44:47]
	v_mfma_f32_16x16x32_bf16 v[40:43], v[160:163], v[202:205], v[40:43]
	v_mfma_f32_16x16x32_bf16 v[36:39], v[152:155], v[210:213], v[36:39]
	v_mfma_f32_16x16x32_bf16 v[32:35], v[160:163], v[210:213], v[32:35]
	s_setprio 0
	s_setprio 1
	v_mfma_f32_16x16x32_bf16 v[28:31], v[166:169], v[182:185], v[28:31]
	v_mfma_f32_16x16x32_bf16 v[24:27], v[174:177], v[182:185], v[24:27]
	v_mfma_f32_16x16x32_bf16 v[20:23], v[166:169], v[190:193], v[20:23]
	v_mfma_f32_16x16x32_bf16 v[16:19], v[174:177], v[190:193], v[16:19]
	v_mfma_f32_16x16x32_bf16 v[12:15], v[166:169], v[198:201], v[12:15]
	v_mfma_f32_16x16x32_bf16 v[8:11], v[174:177], v[198:201], v[8:11]
	v_mfma_f32_16x16x32_bf16 v[4:7], v[166:169], v[206:209], v[4:7]
	v_mfma_f32_16x16x32_bf16 v[0:3], v[174:177], v[206:209], v[0:3]
	v_mfma_f32_16x16x32_bf16 v[28:31], v[170:173], v[186:189], v[28:31]
	v_mfma_f32_16x16x32_bf16 v[24:27], v[178:181], v[186:189], v[24:27]
	v_mfma_f32_16x16x32_bf16 v[20:23], v[170:173], v[194:197], v[20:23]
	v_mfma_f32_16x16x32_bf16 v[16:19], v[178:181], v[194:197], v[16:19]
	v_mfma_f32_16x16x32_bf16 v[12:15], v[170:173], v[202:205], v[12:15]
	v_mfma_f32_16x16x32_bf16 v[8:11], v[178:181], v[202:205], v[8:11]
	v_mfma_f32_16x16x32_bf16 v[4:7], v[170:173], v[210:213], v[4:7]
	v_mfma_f32_16x16x32_bf16 v[0:3], v[178:181], v[210:213], v[0:3]
	s_setprio 0
	s_barrier
	s_add_i32 s41, s41, 2
	s_add_u32 s28, s28, 0x100
	s_addc_u32 s29, s29, 0
	s_add_u32 s4, s4, 0x100
	s_addc_u32 s39, s39, 0
	s_cmp_gt_u32 s41, 13
	s_cbranch_scc0 .LBB0_545
	s_and_b64 vcc, exec, s[10:11]
	s_cbranch_vccz .LBB0_548
	s_barrier
